# idx phase: hand-written score pass with all key tiles requested up front; top-k counting through bf16 MFMA of exact 0/1 indicators
# speedup vs baseline: 1.0586x; 1.0071x over previous
.LBB0_810:
	v_readlane_b32 s0, v252, 1
	v_readlane_b32 s1, v252, 2
	s_bitcmp0_b32 s34, 0
	v_readlane_b32 s1, v252, 0
	v_readlane_b32 s4, v253, 26
	s_mul_i32 s0, s34, s0
	s_cselect_b32 s1, s1, s4
	s_add_i32 s0, s1, s0
	s_cmpk_gt_i32 s0, 0x3ff
	s_cbranch_scc1 .LBB0_809
	s_lshr_b32 s1, s0, 3
	s_and_b32 s5, s0, 7
	s_sub_i32 s4, 0x7f, s1
	s_lshl_b32 s33, s4, 4
	s_lshl_b32 s28, s5, 11
	s_add_i32 s6, s33, s28
	v_readlane_b32 s5, v252, 5
	v_and_b32_e32 v0, 15, v197
	v_lshrrev_b32_e32 v1, 4, v197
	v_add_u32_e32 v242, s6, v0
	v_lshlrev_b32_e32 v2, 4, v1
	v_lshl_add_u32 v243, v242, 9, v2
	v_lshlrev_b32_e32 v244, 6, v242
	v_add_u32_e32 v3, s28, v0
	v_lshl_add_u32 v245, v3, 7, v2
	s_lshr_b32 s5, s5, 6
	s_add_u32 s36, s40, 0x10e00000
	s_addc_u32 s37, s41, 0
	s_add_u32 s38, s40, 0x12e00000
	s_addc_u32 s39, s41, 0
	s_add_u32 s42, s40, 0x11600000
	s_addc_u32 s43, s41, 0
	s_lshl_b32 s7, s5, 2
	s_lshl_b32 s0, s5, 13
	v_add_u32_e32 v245, s0, v245
	v_add_u32_e32 v246, 0x1000, v245
	v_mov_b32_e32 v3, 0x2010
	v_mul_lo_u32 v247, v0, v3
	v_lshl_add_u32 v247, v1, 4, v247
	s_lshl_b32 s0, s7, 6
	v_add_u32_e32 v247, s0, v247
	s_waitcnt vmcnt(0) lgkmcnt(0)
	global_load_dwordx4 v[0:3], v243, s[36:37]
	global_load_dwordx4 v[4:7], v243, s[36:37] offset:64
	global_load_dwordx4 v[8:11], v243, s[36:37] offset:128
	global_load_dwordx4 v[12:15], v243, s[36:37] offset:192
	global_load_dwordx4 v[16:19], v243, s[36:37] offset:256
	global_load_dwordx4 v[20:23], v243, s[36:37] offset:320
	global_load_dwordx4 v[24:27], v243, s[36:37] offset:384
	global_load_dwordx4 v[28:31], v243, s[36:37] offset:448
	global_load_dwordx4 v[164:167], v244, s[38:39] offset:32
	s_sub_i32 s0, s4, s7
	s_cmp_lt_i32 s0, 0
	s_cbranch_scc1 .LBB0_820
	s_lshr_b32 s0, s0, 5
	s_cmp_eq_u32 s0, 0
	s_cbranch_scc1 .Lsc_g1
	s_cmp_eq_u32 s0, 1
	s_cbranch_scc1 .Lsc_g2
	s_cmp_eq_u32 s0, 2
	s_cbranch_scc1 .Lsc_g3
.Lsc_g4:
	global_load_dwordx4 v[32:35], v245, s[42:43]
	global_load_dwordx4 v[36:39], v245, s[42:43] offset:64
	global_load_dwordx4 v[40:43], v245, s[42:43] offset:2048
	global_load_dwordx4 v[44:47], v245, s[42:43] offset:2112
	global_load_dwordx4 v[48:51], v246, s[42:43]
	global_load_dwordx4 v[52:55], v246, s[42:43] offset:64
	global_load_dwordx4 v[56:59], v246, s[42:43] offset:2048
	global_load_dwordx4 v[60:63], v246, s[42:43] offset:2112
	v_add_u32_e32 v245, 0x10000, v245
	v_add_u32_e32 v246, 0x10000, v246
	global_load_dwordx4 v[64:67], v245, s[42:43]
	global_load_dwordx4 v[68:71], v245, s[42:43] offset:64
	global_load_dwordx4 v[72:75], v245, s[42:43] offset:2048
	global_load_dwordx4 v[76:79], v245, s[42:43] offset:2112
	global_load_dwordx4 v[80:83], v246, s[42:43]
	global_load_dwordx4 v[84:87], v246, s[42:43] offset:64
	global_load_dwordx4 v[88:91], v246, s[42:43] offset:2048
	global_load_dwordx4 v[92:95], v246, s[42:43] offset:2112
	v_add_u32_e32 v245, 0x10000, v245
	v_add_u32_e32 v246, 0x10000, v246
	global_load_dwordx4 v[96:99], v245, s[42:43]
	global_load_dwordx4 v[100:103], v245, s[42:43] offset:64
	global_load_dwordx4 v[104:107], v245, s[42:43] offset:2048
	global_load_dwordx4 v[108:111], v245, s[42:43] offset:2112
	global_load_dwordx4 v[112:115], v246, s[42:43]
	global_load_dwordx4 v[116:119], v246, s[42:43] offset:64
	global_load_dwordx4 v[120:123], v246, s[42:43] offset:2048
	global_load_dwordx4 v[124:127], v246, s[42:43] offset:2112
	v_add_u32_e32 v245, 0x10000, v245
	v_add_u32_e32 v246, 0x10000, v246
	global_load_dwordx4 v[128:131], v245, s[42:43]
	global_load_dwordx4 v[132:135], v245, s[42:43] offset:64
	global_load_dwordx4 v[136:139], v245, s[42:43] offset:2048
	global_load_dwordx4 v[140:143], v245, s[42:43] offset:2112
	global_load_dwordx4 v[144:147], v246, s[42:43]
	global_load_dwordx4 v[148:151], v246, s[42:43] offset:64
	global_load_dwordx4 v[152:155], v246, s[42:43] offset:2048
	global_load_dwordx4 v[156:159], v246, s[42:43] offset:2112
	s_waitcnt vmcnt(30)
	v_mfma_f32_16x16x32_bf16 v[168:171], v[32:35], v[0:3], 0
	v_mfma_f32_16x16x32_bf16 v[172:175], v[32:35], v[8:11], 0
	v_mfma_f32_16x16x32_bf16 v[176:179], v[32:35], v[16:19], 0
	v_mfma_f32_16x16x32_bf16 v[180:183], v[32:35], v[24:27], 0
	v_mfma_f32_16x16x32_bf16 v[168:171], v[36:39], v[4:7], v[168:171]
	v_mfma_f32_16x16x32_bf16 v[172:175], v[36:39], v[12:15], v[172:175]
	v_mfma_f32_16x16x32_bf16 v[176:179], v[36:39], v[20:23], v[176:179]
	v_mfma_f32_16x16x32_bf16 v[180:183], v[36:39], v[28:31], v[180:183]
	s_waitcnt vmcnt(28)
	v_mfma_f32_16x16x32_bf16 v[184:187], v[40:43], v[0:3], 0
	v_mfma_f32_16x16x32_bf16 v[188:191], v[40:43], v[8:11], 0
	v_mfma_f32_16x16x32_bf16 v[226:229], v[40:43], v[16:19], 0
	v_mfma_f32_16x16x32_bf16 v[230:233], v[40:43], v[24:27], 0
	v_mfma_f32_16x16x32_bf16 v[184:187], v[44:47], v[4:7], v[184:187]
	v_mfma_f32_16x16x32_bf16 v[188:191], v[44:47], v[12:15], v[188:191]
	v_mfma_f32_16x16x32_bf16 v[226:229], v[44:47], v[20:23], v[226:229]
	v_mfma_f32_16x16x32_bf16 v[230:233], v[44:47], v[28:31], v[230:233]
	v_max_f32_e32 v168, 0, v168
	v_max_f32_e32 v169, 0, v169
	v_max_f32_e32 v170, 0, v170
	v_max_f32_e32 v171, 0, v171
	v_max_f32_e32 v172, 0, v172
	v_max_f32_e32 v173, 0, v173
	v_max_f32_e32 v174, 0, v174
	v_max_f32_e32 v175, 0, v175
	v_max_f32_e32 v176, 0, v176
	v_max_f32_e32 v177, 0, v177
	v_max_f32_e32 v178, 0, v178
	v_max_f32_e32 v179, 0, v179
	v_max_f32_e32 v180, 0, v180
	v_max_f32_e32 v181, 0, v181
	v_max_f32_e32 v182, 0, v182
	v_max_f32_e32 v183, 0, v183
	v_fma_f32 v234, v164, v168, 0
	v_fma_f32 v235, v164, v169, 0
	v_fma_f32 v236, v164, v170, 0
	v_fma_f32 v237, v164, v171, 0
	v_fmac_f32_e32 v234, v165, v172
	v_fmac_f32_e32 v235, v165, v173
	v_fmac_f32_e32 v236, v165, v174
	v_fmac_f32_e32 v237, v165, v175
	v_fmac_f32_e32 v234, v166, v176
	v_fmac_f32_e32 v235, v166, v177
	v_fmac_f32_e32 v236, v166, v178
	v_fmac_f32_e32 v237, v166, v179
	v_fmac_f32_e32 v234, v167, v180
	v_fmac_f32_e32 v235, v167, v181
	v_fmac_f32_e32 v236, v167, v182
	v_fmac_f32_e32 v237, v167, v183
	ds_write_b128 v247, v[234:237] offset:0
	s_waitcnt vmcnt(26)
	v_mfma_f32_16x16x32_bf16 v[168:171], v[48:51], v[0:3], 0
	v_mfma_f32_16x16x32_bf16 v[172:175], v[48:51], v[8:11], 0
	v_mfma_f32_16x16x32_bf16 v[176:179], v[48:51], v[16:19], 0
	v_mfma_f32_16x16x32_bf16 v[180:183], v[48:51], v[24:27], 0
	v_mfma_f32_16x16x32_bf16 v[168:171], v[52:55], v[4:7], v[168:171]
	v_mfma_f32_16x16x32_bf16 v[172:175], v[52:55], v[12:15], v[172:175]
	v_mfma_f32_16x16x32_bf16 v[176:179], v[52:55], v[20:23], v[176:179]
	v_mfma_f32_16x16x32_bf16 v[180:183], v[52:55], v[28:31], v[180:183]
	v_max_f32_e32 v184, 0, v184
	v_max_f32_e32 v185, 0, v185
	v_max_f32_e32 v186, 0, v186
	v_max_f32_e32 v187, 0, v187
	v_max_f32_e32 v188, 0, v188
	v_max_f32_e32 v189, 0, v189
	v_max_f32_e32 v190, 0, v190
	v_max_f32_e32 v191, 0, v191
	v_max_f32_e32 v226, 0, v226
	v_max_f32_e32 v227, 0, v227
	v_max_f32_e32 v228, 0, v228
	v_max_f32_e32 v229, 0, v229
	v_max_f32_e32 v230, 0, v230
	v_max_f32_e32 v231, 0, v231
	v_max_f32_e32 v232, 0, v232
	v_max_f32_e32 v233, 0, v233
	v_fma_f32 v238, v164, v184, 0
	v_fma_f32 v239, v164, v185, 0
	v_fma_f32 v240, v164, v186, 0
	v_fma_f32 v241, v164, v187, 0
	v_fmac_f32_e32 v238, v165, v188
	v_fmac_f32_e32 v239, v165, v189
	v_fmac_f32_e32 v240, v165, v190
	v_fmac_f32_e32 v241, v165, v191
	v_fmac_f32_e32 v238, v166, v226
	v_fmac_f32_e32 v239, v166, v227
	v_fmac_f32_e32 v240, v166, v228
	v_fmac_f32_e32 v241, v166, v229
	v_fmac_f32_e32 v238, v167, v230
	v_fmac_f32_e32 v239, v167, v231
	v_fmac_f32_e32 v240, v167, v232
	v_fmac_f32_e32 v241, v167, v233
	ds_write_b128 v247, v[238:241] offset:64
	s_waitcnt vmcnt(24)
	v_mfma_f32_16x16x32_bf16 v[184:187], v[56:59], v[0:3], 0
	v_mfma_f32_16x16x32_bf16 v[188:191], v[56:59], v[8:11], 0
	v_mfma_f32_16x16x32_bf16 v[226:229], v[56:59], v[16:19], 0
	v_mfma_f32_16x16x32_bf16 v[230:233], v[56:59], v[24:27], 0
	v_mfma_f32_16x16x32_bf16 v[184:187], v[60:63], v[4:7], v[184:187]
	v_mfma_f32_16x16x32_bf16 v[188:191], v[60:63], v[12:15], v[188:191]
	v_mfma_f32_16x16x32_bf16 v[226:229], v[60:63], v[20:23], v[226:229]
	v_mfma_f32_16x16x32_bf16 v[230:233], v[60:63], v[28:31], v[230:233]
	v_max_f32_e32 v168, 0, v168
	v_max_f32_e32 v169, 0, v169
	v_max_f32_e32 v170, 0, v170
	v_max_f32_e32 v171, 0, v171
	v_max_f32_e32 v172, 0, v172
	v_max_f32_e32 v173, 0, v173
	v_max_f32_e32 v174, 0, v174
	v_max_f32_e32 v175, 0, v175
	v_max_f32_e32 v176, 0, v176
	v_max_f32_e32 v177, 0, v177
	v_max_f32_e32 v178, 0, v178
	v_max_f32_e32 v179, 0, v179
	v_max_f32_e32 v180, 0, v180
	v_max_f32_e32 v181, 0, v181
	v_max_f32_e32 v182, 0, v182
	v_max_f32_e32 v183, 0, v183
	v_fma_f32 v234, v164, v168, 0
	v_fma_f32 v235, v164, v169, 0
	v_fma_f32 v236, v164, v170, 0
	v_fma_f32 v237, v164, v171, 0
	v_fmac_f32_e32 v234, v165, v172
	v_fmac_f32_e32 v235, v165, v173
	v_fmac_f32_e32 v236, v165, v174
	v_fmac_f32_e32 v237, v165, v175
	v_fmac_f32_e32 v234, v166, v176
	v_fmac_f32_e32 v235, v166, v177
	v_fmac_f32_e32 v236, v166, v178
	v_fmac_f32_e32 v237, v166, v179
	v_fmac_f32_e32 v234, v167, v180
	v_fmac_f32_e32 v235, v167, v181
	v_fmac_f32_e32 v236, v167, v182
	v_fmac_f32_e32 v237, v167, v183
	ds_write_b128 v247, v[234:237] offset:128
	s_waitcnt vmcnt(22)
	v_mfma_f32_16x16x32_bf16 v[168:171], v[64:67], v[0:3], 0
	v_mfma_f32_16x16x32_bf16 v[172:175], v[64:67], v[8:11], 0
	v_mfma_f32_16x16x32_bf16 v[176:179], v[64:67], v[16:19], 0
	v_mfma_f32_16x16x32_bf16 v[180:183], v[64:67], v[24:27], 0
	v_mfma_f32_16x16x32_bf16 v[168:171], v[68:71], v[4:7], v[168:171]
	v_mfma_f32_16x16x32_bf16 v[172:175], v[68:71], v[12:15], v[172:175]
	v_mfma_f32_16x16x32_bf16 v[176:179], v[68:71], v[20:23], v[176:179]
	v_mfma_f32_16x16x32_bf16 v[180:183], v[68:71], v[28:31], v[180:183]
	v_max_f32_e32 v184, 0, v184
	v_max_f32_e32 v185, 0, v185
	v_max_f32_e32 v186, 0, v186
	v_max_f32_e32 v187, 0, v187
	v_max_f32_e32 v188, 0, v188
	v_max_f32_e32 v189, 0, v189
	v_max_f32_e32 v190, 0, v190
	v_max_f32_e32 v191, 0, v191
	v_max_f32_e32 v226, 0, v226
	v_max_f32_e32 v227, 0, v227
	v_max_f32_e32 v228, 0, v228
	v_max_f32_e32 v229, 0, v229
	v_max_f32_e32 v230, 0, v230
	v_max_f32_e32 v231, 0, v231
	v_max_f32_e32 v232, 0, v232
	v_max_f32_e32 v233, 0, v233
	v_fma_f32 v238, v164, v184, 0
	v_fma_f32 v239, v164, v185, 0
	v_fma_f32 v240, v164, v186, 0
	v_fma_f32 v241, v164, v187, 0
	v_fmac_f32_e32 v238, v165, v188
	v_fmac_f32_e32 v239, v165, v189
	v_fmac_f32_e32 v240, v165, v190
	v_fmac_f32_e32 v241, v165, v191
	v_fmac_f32_e32 v238, v166, v226
	v_fmac_f32_e32 v239, v166, v227
	v_fmac_f32_e32 v240, v166, v228
	v_fmac_f32_e32 v241, v166, v229
	v_fmac_f32_e32 v238, v167, v230
	v_fmac_f32_e32 v239, v167, v231
	v_fmac_f32_e32 v240, v167, v232
	v_fmac_f32_e32 v241, v167, v233
	ds_write_b128 v247, v[238:241] offset:192
	s_waitcnt vmcnt(20)
	v_mfma_f32_16x16x32_bf16 v[184:187], v[72:75], v[0:3], 0
	v_mfma_f32_16x16x32_bf16 v[188:191], v[72:75], v[8:11], 0
	v_mfma_f32_16x16x32_bf16 v[226:229], v[72:75], v[16:19], 0
	v_mfma_f32_16x16x32_bf16 v[230:233], v[72:75], v[24:27], 0
	v_mfma_f32_16x16x32_bf16 v[184:187], v[76:79], v[4:7], v[184:187]
	v_mfma_f32_16x16x32_bf16 v[188:191], v[76:79], v[12:15], v[188:191]
	v_mfma_f32_16x16x32_bf16 v[226:229], v[76:79], v[20:23], v[226:229]
	v_mfma_f32_16x16x32_bf16 v[230:233], v[76:79], v[28:31], v[230:233]
	v_max_f32_e32 v168, 0, v168
	v_max_f32_e32 v169, 0, v169
	v_max_f32_e32 v170, 0, v170
	v_max_f32_e32 v171, 0, v171
	v_max_f32_e32 v172, 0, v172
	v_max_f32_e32 v173, 0, v173
	v_max_f32_e32 v174, 0, v174
	v_max_f32_e32 v175, 0, v175
	v_max_f32_e32 v176, 0, v176
	v_max_f32_e32 v177, 0, v177
	v_max_f32_e32 v178, 0, v178
	v_max_f32_e32 v179, 0, v179
	v_max_f32_e32 v180, 0, v180
	v_max_f32_e32 v181, 0, v181
	v_max_f32_e32 v182, 0, v182
	v_max_f32_e32 v183, 0, v183
	v_fma_f32 v234, v164, v168, 0
	v_fma_f32 v235, v164, v169, 0
	v_fma_f32 v236, v164, v170, 0
	v_fma_f32 v237, v164, v171, 0
	v_fmac_f32_e32 v234, v165, v172
	v_fmac_f32_e32 v235, v165, v173
	v_fmac_f32_e32 v236, v165, v174
	v_fmac_f32_e32 v237, v165, v175
	v_fmac_f32_e32 v234, v166, v176
	v_fmac_f32_e32 v235, v166, v177
	v_fmac_f32_e32 v236, v166, v178
	v_fmac_f32_e32 v237, v166, v179
	v_fmac_f32_e32 v234, v167, v180
	v_fmac_f32_e32 v235, v167, v181
	v_fmac_f32_e32 v236, v167, v182
	v_fmac_f32_e32 v237, v167, v183
	ds_write_b128 v247, v[234:237] offset:2048
	s_waitcnt vmcnt(18)
	v_mfma_f32_16x16x32_bf16 v[168:171], v[80:83], v[0:3], 0
	v_mfma_f32_16x16x32_bf16 v[172:175], v[80:83], v[8:11], 0
	v_mfma_f32_16x16x32_bf16 v[176:179], v[80:83], v[16:19], 0
	v_mfma_f32_16x16x32_bf16 v[180:183], v[80:83], v[24:27], 0
	v_mfma_f32_16x16x32_bf16 v[168:171], v[84:87], v[4:7], v[168:171]
	v_mfma_f32_16x16x32_bf16 v[172:175], v[84:87], v[12:15], v[172:175]
	v_mfma_f32_16x16x32_bf16 v[176:179], v[84:87], v[20:23], v[176:179]
	v_mfma_f32_16x16x32_bf16 v[180:183], v[84:87], v[28:31], v[180:183]
	v_max_f32_e32 v184, 0, v184
	v_max_f32_e32 v185, 0, v185
	v_max_f32_e32 v186, 0, v186
	v_max_f32_e32 v187, 0, v187
	v_max_f32_e32 v188, 0, v188
	v_max_f32_e32 v189, 0, v189
	v_max_f32_e32 v190, 0, v190
	v_max_f32_e32 v191, 0, v191
	v_max_f32_e32 v226, 0, v226
	v_max_f32_e32 v227, 0, v227
	v_max_f32_e32 v228, 0, v228
	v_max_f32_e32 v229, 0, v229
	v_max_f32_e32 v230, 0, v230
	v_max_f32_e32 v231, 0, v231
	v_max_f32_e32 v232, 0, v232
	v_max_f32_e32 v233, 0, v233
	v_fma_f32 v238, v164, v184, 0
	v_fma_f32 v239, v164, v185, 0
	v_fma_f32 v240, v164, v186, 0
	v_fma_f32 v241, v164, v187, 0
	v_fmac_f32_e32 v238, v165, v188
	v_fmac_f32_e32 v239, v165, v189
	v_fmac_f32_e32 v240, v165, v190
	v_fmac_f32_e32 v241, v165, v191
	v_fmac_f32_e32 v238, v166, v226
	v_fmac_f32_e32 v239, v166, v227
	v_fmac_f32_e32 v240, v166, v228
	v_fmac_f32_e32 v241, v166, v229
	v_fmac_f32_e32 v238, v167, v230
	v_fmac_f32_e32 v239, v167, v231
	v_fmac_f32_e32 v240, v167, v232
	v_fmac_f32_e32 v241, v167, v233
	ds_write_b128 v247, v[238:241] offset:2112
	s_waitcnt vmcnt(16)
	v_mfma_f32_16x16x32_bf16 v[184:187], v[88:91], v[0:3], 0
	v_mfma_f32_16x16x32_bf16 v[188:191], v[88:91], v[8:11], 0
	v_mfma_f32_16x16x32_bf16 v[226:229], v[88:91], v[16:19], 0
	v_mfma_f32_16x16x32_bf16 v[230:233], v[88:91], v[24:27], 0
	v_mfma_f32_16x16x32_bf16 v[184:187], v[92:95], v[4:7], v[184:187]
	v_mfma_f32_16x16x32_bf16 v[188:191], v[92:95], v[12:15], v[188:191]
	v_mfma_f32_16x16x32_bf16 v[226:229], v[92:95], v[20:23], v[226:229]
	v_mfma_f32_16x16x32_bf16 v[230:233], v[92:95], v[28:31], v[230:233]
	v_max_f32_e32 v168, 0, v168
	v_max_f32_e32 v169, 0, v169
	v_max_f32_e32 v170, 0, v170
	v_max_f32_e32 v171, 0, v171
	v_max_f32_e32 v172, 0, v172
	v_max_f32_e32 v173, 0, v173
	v_max_f32_e32 v174, 0, v174
	v_max_f32_e32 v175, 0, v175
	v_max_f32_e32 v176, 0, v176
	v_max_f32_e32 v177, 0, v177
	v_max_f32_e32 v178, 0, v178
	v_max_f32_e32 v179, 0, v179
	v_max_f32_e32 v180, 0, v180
	v_max_f32_e32 v181, 0, v181
	v_max_f32_e32 v182, 0, v182
	v_max_f32_e32 v183, 0, v183
	v_fma_f32 v234, v164, v168, 0
	v_fma_f32 v235, v164, v169, 0
	v_fma_f32 v236, v164, v170, 0
	v_fma_f32 v237, v164, v171, 0
	v_fmac_f32_e32 v234, v165, v172
	v_fmac_f32_e32 v235, v165, v173
	v_fmac_f32_e32 v236, v165, v174
	v_fmac_f32_e32 v237, v165, v175
	v_fmac_f32_e32 v234, v166, v176
	v_fmac_f32_e32 v235, v166, v177
	v_fmac_f32_e32 v236, v166, v178
	v_fmac_f32_e32 v237, v166, v179
	v_fmac_f32_e32 v234, v167, v180
	v_fmac_f32_e32 v235, v167, v181
	v_fmac_f32_e32 v236, v167, v182
	v_fmac_f32_e32 v237, v167, v183
	ds_write_b128 v247, v[234:237] offset:2176
	s_waitcnt vmcnt(14)
	v_mfma_f32_16x16x32_bf16 v[168:171], v[96:99], v[0:3], 0
	v_mfma_f32_16x16x32_bf16 v[172:175], v[96:99], v[8:11], 0
	v_mfma_f32_16x16x32_bf16 v[176:179], v[96:99], v[16:19], 0
	v_mfma_f32_16x16x32_bf16 v[180:183], v[96:99], v[24:27], 0
	v_mfma_f32_16x16x32_bf16 v[168:171], v[100:103], v[4:7], v[168:171]
	v_mfma_f32_16x16x32_bf16 v[172:175], v[100:103], v[12:15], v[172:175]
	v_mfma_f32_16x16x32_bf16 v[176:179], v[100:103], v[20:23], v[176:179]
	v_mfma_f32_16x16x32_bf16 v[180:183], v[100:103], v[28:31], v[180:183]
	v_max_f32_e32 v184, 0, v184
	v_max_f32_e32 v185, 0, v185
	v_max_f32_e32 v186, 0, v186
	v_max_f32_e32 v187, 0, v187
	v_max_f32_e32 v188, 0, v188
	v_max_f32_e32 v189, 0, v189
	v_max_f32_e32 v190, 0, v190
	v_max_f32_e32 v191, 0, v191
	v_max_f32_e32 v226, 0, v226
	v_max_f32_e32 v227, 0, v227
	v_max_f32_e32 v228, 0, v228
	v_max_f32_e32 v229, 0, v229
	v_max_f32_e32 v230, 0, v230
	v_max_f32_e32 v231, 0, v231
	v_max_f32_e32 v232, 0, v232
	v_max_f32_e32 v233, 0, v233
	v_fma_f32 v238, v164, v184, 0
	v_fma_f32 v239, v164, v185, 0
	v_fma_f32 v240, v164, v186, 0
	v_fma_f32 v241, v164, v187, 0
	v_fmac_f32_e32 v238, v165, v188
	v_fmac_f32_e32 v239, v165, v189
	v_fmac_f32_e32 v240, v165, v190
	v_fmac_f32_e32 v241, v165, v191
	v_fmac_f32_e32 v238, v166, v226
	v_fmac_f32_e32 v239, v166, v227
	v_fmac_f32_e32 v240, v166, v228
	v_fmac_f32_e32 v241, v166, v229
	v_fmac_f32_e32 v238, v167, v230
	v_fmac_f32_e32 v239, v167, v231
	v_fmac_f32_e32 v240, v167, v232
	v_fmac_f32_e32 v241, v167, v233
	ds_write_b128 v247, v[238:241] offset:2240
	s_waitcnt vmcnt(12)
	v_mfma_f32_16x16x32_bf16 v[184:187], v[104:107], v[0:3], 0
	v_mfma_f32_16x16x32_bf16 v[188:191], v[104:107], v[8:11], 0
	v_mfma_f32_16x16x32_bf16 v[226:229], v[104:107], v[16:19], 0
	v_mfma_f32_16x16x32_bf16 v[230:233], v[104:107], v[24:27], 0
	v_mfma_f32_16x16x32_bf16 v[184:187], v[108:111], v[4:7], v[184:187]
	v_mfma_f32_16x16x32_bf16 v[188:191], v[108:111], v[12:15], v[188:191]
	v_mfma_f32_16x16x32_bf16 v[226:229], v[108:111], v[20:23], v[226:229]
	v_mfma_f32_16x16x32_bf16 v[230:233], v[108:111], v[28:31], v[230:233]
	v_max_f32_e32 v168, 0, v168
	v_max_f32_e32 v169, 0, v169
	v_max_f32_e32 v170, 0, v170
	v_max_f32_e32 v171, 0, v171
	v_max_f32_e32 v172, 0, v172
	v_max_f32_e32 v173, 0, v173
	v_max_f32_e32 v174, 0, v174
	v_max_f32_e32 v175, 0, v175
	v_max_f32_e32 v176, 0, v176
	v_max_f32_e32 v177, 0, v177
	v_max_f32_e32 v178, 0, v178
	v_max_f32_e32 v179, 0, v179
	v_max_f32_e32 v180, 0, v180
	v_max_f32_e32 v181, 0, v181
	v_max_f32_e32 v182, 0, v182
	v_max_f32_e32 v183, 0, v183
	v_fma_f32 v234, v164, v168, 0
	v_fma_f32 v235, v164, v169, 0
	v_fma_f32 v236, v164, v170, 0
	v_fma_f32 v237, v164, v171, 0
	v_fmac_f32_e32 v234, v165, v172
	v_fmac_f32_e32 v235, v165, v173
	v_fmac_f32_e32 v236, v165, v174
	v_fmac_f32_e32 v237, v165, v175
	v_fmac_f32_e32 v234, v166, v176
	v_fmac_f32_e32 v235, v166, v177
	v_fmac_f32_e32 v236, v166, v178
	v_fmac_f32_e32 v237, v166, v179
	v_fmac_f32_e32 v234, v167, v180
	v_fmac_f32_e32 v235, v167, v181
	v_fmac_f32_e32 v236, v167, v182
	v_fmac_f32_e32 v237, v167, v183
	ds_write_b128 v247, v[234:237] offset:4096
	s_waitcnt vmcnt(10)
	v_mfma_f32_16x16x32_bf16 v[168:171], v[112:115], v[0:3], 0
	v_mfma_f32_16x16x32_bf16 v[172:175], v[112:115], v[8:11], 0
	v_mfma_f32_16x16x32_bf16 v[176:179], v[112:115], v[16:19], 0
	v_mfma_f32_16x16x32_bf16 v[180:183], v[112:115], v[24:27], 0
	v_mfma_f32_16x16x32_bf16 v[168:171], v[116:119], v[4:7], v[168:171]
	v_mfma_f32_16x16x32_bf16 v[172:175], v[116:119], v[12:15], v[172:175]
	v_mfma_f32_16x16x32_bf16 v[176:179], v[116:119], v[20:23], v[176:179]
	v_mfma_f32_16x16x32_bf16 v[180:183], v[116:119], v[28:31], v[180:183]
	v_max_f32_e32 v184, 0, v184
	v_max_f32_e32 v185, 0, v185
	v_max_f32_e32 v186, 0, v186
	v_max_f32_e32 v187, 0, v187
	v_max_f32_e32 v188, 0, v188
	v_max_f32_e32 v189, 0, v189
	v_max_f32_e32 v190, 0, v190
	v_max_f32_e32 v191, 0, v191
	v_max_f32_e32 v226, 0, v226
	v_max_f32_e32 v227, 0, v227
	v_max_f32_e32 v228, 0, v228
	v_max_f32_e32 v229, 0, v229
	v_max_f32_e32 v230, 0, v230
	v_max_f32_e32 v231, 0, v231
	v_max_f32_e32 v232, 0, v232
	v_max_f32_e32 v233, 0, v233
	v_fma_f32 v238, v164, v184, 0
	v_fma_f32 v239, v164, v185, 0
	v_fma_f32 v240, v164, v186, 0
	v_fma_f32 v241, v164, v187, 0
	v_fmac_f32_e32 v238, v165, v188
	v_fmac_f32_e32 v239, v165, v189
	v_fmac_f32_e32 v240, v165, v190
	v_fmac_f32_e32 v241, v165, v191
	v_fmac_f32_e32 v238, v166, v226
	v_fmac_f32_e32 v239, v166, v227
	v_fmac_f32_e32 v240, v166, v228
	v_fmac_f32_e32 v241, v166, v229
	v_fmac_f32_e32 v238, v167, v230
	v_fmac_f32_e32 v239, v167, v231
	v_fmac_f32_e32 v240, v167, v232
	v_fmac_f32_e32 v241, v167, v233
	ds_write_b128 v247, v[238:241] offset:4160
	s_waitcnt vmcnt(8)
	v_mfma_f32_16x16x32_bf16 v[184:187], v[120:123], v[0:3], 0
	v_mfma_f32_16x16x32_bf16 v[188:191], v[120:123], v[8:11], 0
	v_mfma_f32_16x16x32_bf16 v[226:229], v[120:123], v[16:19], 0
	v_mfma_f32_16x16x32_bf16 v[230:233], v[120:123], v[24:27], 0
	v_mfma_f32_16x16x32_bf16 v[184:187], v[124:127], v[4:7], v[184:187]
	v_mfma_f32_16x16x32_bf16 v[188:191], v[124:127], v[12:15], v[188:191]
	v_mfma_f32_16x16x32_bf16 v[226:229], v[124:127], v[20:23], v[226:229]
	v_mfma_f32_16x16x32_bf16 v[230:233], v[124:127], v[28:31], v[230:233]
	v_max_f32_e32 v168, 0, v168
	v_max_f32_e32 v169, 0, v169
	v_max_f32_e32 v170, 0, v170
	v_max_f32_e32 v171, 0, v171
	v_max_f32_e32 v172, 0, v172
	v_max_f32_e32 v173, 0, v173
	v_max_f32_e32 v174, 0, v174
	v_max_f32_e32 v175, 0, v175
	v_max_f32_e32 v176, 0, v176
	v_max_f32_e32 v177, 0, v177
	v_max_f32_e32 v178, 0, v178
	v_max_f32_e32 v179, 0, v179
	v_max_f32_e32 v180, 0, v180
	v_max_f32_e32 v181, 0, v181
	v_max_f32_e32 v182, 0, v182
	v_max_f32_e32 v183, 0, v183
	v_fma_f32 v234, v164, v168, 0
	v_fma_f32 v235, v164, v169, 0
	v_fma_f32 v236, v164, v170, 0
	v_fma_f32 v237, v164, v171, 0
	v_fmac_f32_e32 v234, v165, v172
	v_fmac_f32_e32 v235, v165, v173
	v_fmac_f32_e32 v236, v165, v174
	v_fmac_f32_e32 v237, v165, v175
	v_fmac_f32_e32 v234, v166, v176
	v_fmac_f32_e32 v235, v166, v177
	v_fmac_f32_e32 v236, v166, v178
	v_fmac_f32_e32 v237, v166, v179
	v_fmac_f32_e32 v234, v167, v180
	v_fmac_f32_e32 v235, v167, v181
	v_fmac_f32_e32 v236, v167, v182
	v_fmac_f32_e32 v237, v167, v183
	ds_write_b128 v247, v[234:237] offset:4224
	s_waitcnt vmcnt(6)
	v_mfma_f32_16x16x32_bf16 v[168:171], v[128:131], v[0:3], 0
	v_mfma_f32_16x16x32_bf16 v[172:175], v[128:131], v[8:11], 0
	v_mfma_f32_16x16x32_bf16 v[176:179], v[128:131], v[16:19], 0
	v_mfma_f32_16x16x32_bf16 v[180:183], v[128:131], v[24:27], 0
	v_mfma_f32_16x16x32_bf16 v[168:171], v[132:135], v[4:7], v[168:171]
	v_mfma_f32_16x16x32_bf16 v[172:175], v[132:135], v[12:15], v[172:175]
	v_mfma_f32_16x16x32_bf16 v[176:179], v[132:135], v[20:23], v[176:179]
	v_mfma_f32_16x16x32_bf16 v[180:183], v[132:135], v[28:31], v[180:183]
	v_max_f32_e32 v184, 0, v184
	v_max_f32_e32 v185, 0, v185
	v_max_f32_e32 v186, 0, v186
	v_max_f32_e32 v187, 0, v187
	v_max_f32_e32 v188, 0, v188
	v_max_f32_e32 v189, 0, v189
	v_max_f32_e32 v190, 0, v190
	v_max_f32_e32 v191, 0, v191
	v_max_f32_e32 v226, 0, v226
	v_max_f32_e32 v227, 0, v227
	v_max_f32_e32 v228, 0, v228
	v_max_f32_e32 v229, 0, v229
	v_max_f32_e32 v230, 0, v230
	v_max_f32_e32 v231, 0, v231
	v_max_f32_e32 v232, 0, v232
	v_max_f32_e32 v233, 0, v233
	v_fma_f32 v238, v164, v184, 0
	v_fma_f32 v239, v164, v185, 0
	v_fma_f32 v240, v164, v186, 0
	v_fma_f32 v241, v164, v187, 0
	v_fmac_f32_e32 v238, v165, v188
	v_fmac_f32_e32 v239, v165, v189
	v_fmac_f32_e32 v240, v165, v190
	v_fmac_f32_e32 v241, v165, v191
	v_fmac_f32_e32 v238, v166, v226
	v_fmac_f32_e32 v239, v166, v227
	v_fmac_f32_e32 v240, v166, v228
	v_fmac_f32_e32 v241, v166, v229
	v_fmac_f32_e32 v238, v167, v230
	v_fmac_f32_e32 v239, v167, v231
	v_fmac_f32_e32 v240, v167, v232
	v_fmac_f32_e32 v241, v167, v233
	ds_write_b128 v247, v[238:241] offset:4288
	s_add_i32 s0, s7, 97
	s_cmp_gt_i32 s0, s4
	s_cbranch_scc1 .Lsc_x4_13
	s_waitcnt vmcnt(4)
	v_mfma_f32_16x16x32_bf16 v[184:187], v[136:139], v[0:3], 0
	v_mfma_f32_16x16x32_bf16 v[188:191], v[136:139], v[8:11], 0
	v_mfma_f32_16x16x32_bf16 v[226:229], v[136:139], v[16:19], 0
	v_mfma_f32_16x16x32_bf16 v[230:233], v[136:139], v[24:27], 0
	v_mfma_f32_16x16x32_bf16 v[184:187], v[140:143], v[4:7], v[184:187]
	v_mfma_f32_16x16x32_bf16 v[188:191], v[140:143], v[12:15], v[188:191]
	v_mfma_f32_16x16x32_bf16 v[226:229], v[140:143], v[20:23], v[226:229]
	v_mfma_f32_16x16x32_bf16 v[230:233], v[140:143], v[28:31], v[230:233]
	v_max_f32_e32 v168, 0, v168
	v_max_f32_e32 v169, 0, v169
	v_max_f32_e32 v170, 0, v170
	v_max_f32_e32 v171, 0, v171
	v_max_f32_e32 v172, 0, v172
	v_max_f32_e32 v173, 0, v173
	v_max_f32_e32 v174, 0, v174
	v_max_f32_e32 v175, 0, v175
	v_max_f32_e32 v176, 0, v176
	v_max_f32_e32 v177, 0, v177
	v_max_f32_e32 v178, 0, v178
	v_max_f32_e32 v179, 0, v179
	v_max_f32_e32 v180, 0, v180
	v_max_f32_e32 v181, 0, v181
	v_max_f32_e32 v182, 0, v182
	v_max_f32_e32 v183, 0, v183
	v_fma_f32 v234, v164, v168, 0
	v_fma_f32 v235, v164, v169, 0
	v_fma_f32 v236, v164, v170, 0
	v_fma_f32 v237, v164, v171, 0
	v_fmac_f32_e32 v234, v165, v172
	v_fmac_f32_e32 v235, v165, v173
	v_fmac_f32_e32 v236, v165, v174
	v_fmac_f32_e32 v237, v165, v175
	v_fmac_f32_e32 v234, v166, v176
	v_fmac_f32_e32 v235, v166, v177
	v_fmac_f32_e32 v236, v166, v178
	v_fmac_f32_e32 v237, v166, v179
	v_fmac_f32_e32 v234, v167, v180
	v_fmac_f32_e32 v235, v167, v181
	v_fmac_f32_e32 v236, v167, v182
	v_fmac_f32_e32 v237, v167, v183
	ds_write_b128 v247, v[234:237] offset:6144
	s_add_i32 s0, s7, 98
	s_cmp_gt_i32 s0, s4
	s_cbranch_scc1 .Lsc_x4_14
	s_waitcnt vmcnt(2)
	v_mfma_f32_16x16x32_bf16 v[168:171], v[144:147], v[0:3], 0
	v_mfma_f32_16x16x32_bf16 v[172:175], v[144:147], v[8:11], 0
	v_mfma_f32_16x16x32_bf16 v[176:179], v[144:147], v[16:19], 0
	v_mfma_f32_16x16x32_bf16 v[180:183], v[144:147], v[24:27], 0
	v_mfma_f32_16x16x32_bf16 v[168:171], v[148:151], v[4:7], v[168:171]
	v_mfma_f32_16x16x32_bf16 v[172:175], v[148:151], v[12:15], v[172:175]
	v_mfma_f32_16x16x32_bf16 v[176:179], v[148:151], v[20:23], v[176:179]
	v_mfma_f32_16x16x32_bf16 v[180:183], v[148:151], v[28:31], v[180:183]
	v_max_f32_e32 v184, 0, v184
	v_max_f32_e32 v185, 0, v185
	v_max_f32_e32 v186, 0, v186
	v_max_f32_e32 v187, 0, v187
	v_max_f32_e32 v188, 0, v188
	v_max_f32_e32 v189, 0, v189
	v_max_f32_e32 v190, 0, v190
	v_max_f32_e32 v191, 0, v191
	v_max_f32_e32 v226, 0, v226
	v_max_f32_e32 v227, 0, v227
	v_max_f32_e32 v228, 0, v228
	v_max_f32_e32 v229, 0, v229
	v_max_f32_e32 v230, 0, v230
	v_max_f32_e32 v231, 0, v231
	v_max_f32_e32 v232, 0, v232
	v_max_f32_e32 v233, 0, v233
	v_fma_f32 v238, v164, v184, 0
	v_fma_f32 v239, v164, v185, 0
	v_fma_f32 v240, v164, v186, 0
	v_fma_f32 v241, v164, v187, 0
	v_fmac_f32_e32 v238, v165, v188
	v_fmac_f32_e32 v239, v165, v189
	v_fmac_f32_e32 v240, v165, v190
	v_fmac_f32_e32 v241, v165, v191
	v_fmac_f32_e32 v238, v166, v226
	v_fmac_f32_e32 v239, v166, v227
	v_fmac_f32_e32 v240, v166, v228
	v_fmac_f32_e32 v241, v166, v229
	v_fmac_f32_e32 v238, v167, v230
	v_fmac_f32_e32 v239, v167, v231
	v_fmac_f32_e32 v240, v167, v232
	v_fmac_f32_e32 v241, v167, v233
	ds_write_b128 v247, v[238:241] offset:6208
	s_add_i32 s0, s7, 99
	s_cmp_gt_i32 s0, s4
	s_cbranch_scc1 .Lsc_x4_15
	s_waitcnt vmcnt(0)
	v_mfma_f32_16x16x32_bf16 v[184:187], v[152:155], v[0:3], 0
	v_mfma_f32_16x16x32_bf16 v[188:191], v[152:155], v[8:11], 0
	v_mfma_f32_16x16x32_bf16 v[226:229], v[152:155], v[16:19], 0
	v_mfma_f32_16x16x32_bf16 v[230:233], v[152:155], v[24:27], 0
	v_mfma_f32_16x16x32_bf16 v[184:187], v[156:159], v[4:7], v[184:187]
	v_mfma_f32_16x16x32_bf16 v[188:191], v[156:159], v[12:15], v[188:191]
	v_mfma_f32_16x16x32_bf16 v[226:229], v[156:159], v[20:23], v[226:229]
	v_mfma_f32_16x16x32_bf16 v[230:233], v[156:159], v[28:31], v[230:233]
	v_max_f32_e32 v168, 0, v168
	v_max_f32_e32 v169, 0, v169
	v_max_f32_e32 v170, 0, v170
	v_max_f32_e32 v171, 0, v171
	v_max_f32_e32 v172, 0, v172
	v_max_f32_e32 v173, 0, v173
	v_max_f32_e32 v174, 0, v174
	v_max_f32_e32 v175, 0, v175
	v_max_f32_e32 v176, 0, v176
	v_max_f32_e32 v177, 0, v177
	v_max_f32_e32 v178, 0, v178
	v_max_f32_e32 v179, 0, v179
	v_max_f32_e32 v180, 0, v180
	v_max_f32_e32 v181, 0, v181
	v_max_f32_e32 v182, 0, v182
	v_max_f32_e32 v183, 0, v183
	v_fma_f32 v234, v164, v168, 0
	v_fma_f32 v235, v164, v169, 0
	v_fma_f32 v236, v164, v170, 0
	v_fma_f32 v237, v164, v171, 0
	v_fmac_f32_e32 v234, v165, v172
	v_fmac_f32_e32 v235, v165, v173
	v_fmac_f32_e32 v236, v165, v174
	v_fmac_f32_e32 v237, v165, v175
	v_fmac_f32_e32 v234, v166, v176
	v_fmac_f32_e32 v235, v166, v177
	v_fmac_f32_e32 v236, v166, v178
	v_fmac_f32_e32 v237, v166, v179
	v_fmac_f32_e32 v234, v167, v180
	v_fmac_f32_e32 v235, v167, v181
	v_fmac_f32_e32 v236, v167, v182
	v_fmac_f32_e32 v237, v167, v183
	ds_write_b128 v247, v[234:237] offset:6272
	v_max_f32_e32 v184, 0, v184
	v_max_f32_e32 v185, 0, v185
	v_max_f32_e32 v186, 0, v186
	v_max_f32_e32 v187, 0, v187
	v_max_f32_e32 v188, 0, v188
	v_max_f32_e32 v189, 0, v189
	v_max_f32_e32 v190, 0, v190
	v_max_f32_e32 v191, 0, v191
	v_max_f32_e32 v226, 0, v226
	v_max_f32_e32 v227, 0, v227
	v_max_f32_e32 v228, 0, v228
	v_max_f32_e32 v229, 0, v229
	v_max_f32_e32 v230, 0, v230
	v_max_f32_e32 v231, 0, v231
	v_max_f32_e32 v232, 0, v232
	v_max_f32_e32 v233, 0, v233
	v_fma_f32 v238, v164, v184, 0
	v_fma_f32 v239, v164, v185, 0
	v_fma_f32 v240, v164, v186, 0
	v_fma_f32 v241, v164, v187, 0
	v_fmac_f32_e32 v238, v165, v188
	v_fmac_f32_e32 v239, v165, v189
	v_fmac_f32_e32 v240, v165, v190
	v_fmac_f32_e32 v241, v165, v191
	v_fmac_f32_e32 v238, v166, v226
	v_fmac_f32_e32 v239, v166, v227
	v_fmac_f32_e32 v240, v166, v228
	v_fmac_f32_e32 v241, v166, v229
	v_fmac_f32_e32 v238, v167, v230
	v_fmac_f32_e32 v239, v167, v231
	v_fmac_f32_e32 v240, v167, v232
	v_fmac_f32_e32 v241, v167, v233
	ds_write_b128 v247, v[238:241] offset:6336
	s_branch .LBB0_820
.Lsc_x4_13:
	s_nop 9
	v_max_f32_e32 v168, 0, v168
	v_max_f32_e32 v169, 0, v169
	v_max_f32_e32 v170, 0, v170
	v_max_f32_e32 v171, 0, v171
	v_max_f32_e32 v172, 0, v172
	v_max_f32_e32 v173, 0, v173
	v_max_f32_e32 v174, 0, v174
	v_max_f32_e32 v175, 0, v175
	v_max_f32_e32 v176, 0, v176
	v_max_f32_e32 v177, 0, v177
	v_max_f32_e32 v178, 0, v178
	v_max_f32_e32 v179, 0, v179
	v_max_f32_e32 v180, 0, v180
	v_max_f32_e32 v181, 0, v181
	v_max_f32_e32 v182, 0, v182
	v_max_f32_e32 v183, 0, v183
	v_fma_f32 v234, v164, v168, 0
	v_fma_f32 v235, v164, v169, 0
	v_fma_f32 v236, v164, v170, 0
	v_fma_f32 v237, v164, v171, 0
	v_fmac_f32_e32 v234, v165, v172
	v_fmac_f32_e32 v235, v165, v173
	v_fmac_f32_e32 v236, v165, v174
	v_fmac_f32_e32 v237, v165, v175
	v_fmac_f32_e32 v234, v166, v176
	v_fmac_f32_e32 v235, v166, v177
	v_fmac_f32_e32 v236, v166, v178
	v_fmac_f32_e32 v237, v166, v179
	v_fmac_f32_e32 v234, v167, v180
	v_fmac_f32_e32 v235, v167, v181
	v_fmac_f32_e32 v236, v167, v182
	v_fmac_f32_e32 v237, v167, v183
	ds_write_b128 v247, v[234:237] offset:6144
	s_branch .LBB0_820
.Lsc_x4_14:
	s_nop 9
	v_max_f32_e32 v184, 0, v184
	v_max_f32_e32 v185, 0, v185
	v_max_f32_e32 v186, 0, v186
	v_max_f32_e32 v187, 0, v187
	v_max_f32_e32 v188, 0, v188
	v_max_f32_e32 v189, 0, v189
	v_max_f32_e32 v190, 0, v190
	v_max_f32_e32 v191, 0, v191
	v_max_f32_e32 v226, 0, v226
	v_max_f32_e32 v227, 0, v227
	v_max_f32_e32 v228, 0, v228
	v_max_f32_e32 v229, 0, v229
	v_max_f32_e32 v230, 0, v230
	v_max_f32_e32 v231, 0, v231
	v_max_f32_e32 v232, 0, v232
	v_max_f32_e32 v233, 0, v233
	v_fma_f32 v238, v164, v184, 0
	v_fma_f32 v239, v164, v185, 0
	v_fma_f32 v240, v164, v186, 0
	v_fma_f32 v241, v164, v187, 0
	v_fmac_f32_e32 v238, v165, v188
	v_fmac_f32_e32 v239, v165, v189
	v_fmac_f32_e32 v240, v165, v190
	v_fmac_f32_e32 v241, v165, v191
	v_fmac_f32_e32 v238, v166, v226
	v_fmac_f32_e32 v239, v166, v227
	v_fmac_f32_e32 v240, v166, v228
	v_fmac_f32_e32 v241, v166, v229
	v_fmac_f32_e32 v238, v167, v230
	v_fmac_f32_e32 v239, v167, v231
	v_fmac_f32_e32 v240, v167, v232
	v_fmac_f32_e32 v241, v167, v233
	ds_write_b128 v247, v[238:241] offset:6208
	s_branch .LBB0_820
.Lsc_x4_15:
	s_nop 9
	v_max_f32_e32 v168, 0, v168
	v_max_f32_e32 v169, 0, v169
	v_max_f32_e32 v170, 0, v170
	v_max_f32_e32 v171, 0, v171
	v_max_f32_e32 v172, 0, v172
	v_max_f32_e32 v173, 0, v173
	v_max_f32_e32 v174, 0, v174
	v_max_f32_e32 v175, 0, v175
	v_max_f32_e32 v176, 0, v176
	v_max_f32_e32 v177, 0, v177
	v_max_f32_e32 v178, 0, v178
	v_max_f32_e32 v179, 0, v179
	v_max_f32_e32 v180, 0, v180
	v_max_f32_e32 v181, 0, v181
	v_max_f32_e32 v182, 0, v182
	v_max_f32_e32 v183, 0, v183
	v_fma_f32 v234, v164, v168, 0
	v_fma_f32 v235, v164, v169, 0
	v_fma_f32 v236, v164, v170, 0
	v_fma_f32 v237, v164, v171, 0
	v_fmac_f32_e32 v234, v165, v172
	v_fmac_f32_e32 v235, v165, v173
	v_fmac_f32_e32 v236, v165, v174
	v_fmac_f32_e32 v237, v165, v175
	v_fmac_f32_e32 v234, v166, v176
	v_fmac_f32_e32 v235, v166, v177
	v_fmac_f32_e32 v236, v166, v178
	v_fmac_f32_e32 v237, v166, v179
	v_fmac_f32_e32 v234, v167, v180
	v_fmac_f32_e32 v235, v167, v181
	v_fmac_f32_e32 v236, v167, v182
	v_fmac_f32_e32 v237, v167, v183
	ds_write_b128 v247, v[234:237] offset:6272
	s_branch .LBB0_820
.Lsc_g1:
	global_load_dwordx4 v[32:35], v245, s[42:43]
	global_load_dwordx4 v[36:39], v245, s[42:43] offset:64
	global_load_dwordx4 v[40:43], v245, s[42:43] offset:2048
	global_load_dwordx4 v[44:47], v245, s[42:43] offset:2112
	global_load_dwordx4 v[48:51], v246, s[42:43]
	global_load_dwordx4 v[52:55], v246, s[42:43] offset:64
	global_load_dwordx4 v[56:59], v246, s[42:43] offset:2048
	global_load_dwordx4 v[60:63], v246, s[42:43] offset:2112
	s_waitcnt vmcnt(6)
	v_mfma_f32_16x16x32_bf16 v[168:171], v[32:35], v[0:3], 0
	v_mfma_f32_16x16x32_bf16 v[172:175], v[32:35], v[8:11], 0
	v_mfma_f32_16x16x32_bf16 v[176:179], v[32:35], v[16:19], 0
	v_mfma_f32_16x16x32_bf16 v[180:183], v[32:35], v[24:27], 0
	v_mfma_f32_16x16x32_bf16 v[168:171], v[36:39], v[4:7], v[168:171]
	v_mfma_f32_16x16x32_bf16 v[172:175], v[36:39], v[12:15], v[172:175]
	v_mfma_f32_16x16x32_bf16 v[176:179], v[36:39], v[20:23], v[176:179]
	v_mfma_f32_16x16x32_bf16 v[180:183], v[36:39], v[28:31], v[180:183]
	s_add_i32 s0, s7, 1
	s_cmp_gt_i32 s0, s4
	s_cbranch_scc1 .Lsc_x1_1
	s_waitcnt vmcnt(4)
	v_mfma_f32_16x16x32_bf16 v[184:187], v[40:43], v[0:3], 0
	v_mfma_f32_16x16x32_bf16 v[188:191], v[40:43], v[8:11], 0
	v_mfma_f32_16x16x32_bf16 v[226:229], v[40:43], v[16:19], 0
	v_mfma_f32_16x16x32_bf16 v[230:233], v[40:43], v[24:27], 0
	v_mfma_f32_16x16x32_bf16 v[184:187], v[44:47], v[4:7], v[184:187]
	v_mfma_f32_16x16x32_bf16 v[188:191], v[44:47], v[12:15], v[188:191]
	v_mfma_f32_16x16x32_bf16 v[226:229], v[44:47], v[20:23], v[226:229]
	v_mfma_f32_16x16x32_bf16 v[230:233], v[44:47], v[28:31], v[230:233]
	v_max_f32_e32 v168, 0, v168
	v_max_f32_e32 v169, 0, v169
	v_max_f32_e32 v170, 0, v170
	v_max_f32_e32 v171, 0, v171
	v_max_f32_e32 v172, 0, v172
	v_max_f32_e32 v173, 0, v173
	v_max_f32_e32 v174, 0, v174
	v_max_f32_e32 v175, 0, v175
	v_max_f32_e32 v176, 0, v176
	v_max_f32_e32 v177, 0, v177
	v_max_f32_e32 v178, 0, v178
	v_max_f32_e32 v179, 0, v179
	v_max_f32_e32 v180, 0, v180
	v_max_f32_e32 v181, 0, v181
	v_max_f32_e32 v182, 0, v182
	v_max_f32_e32 v183, 0, v183
	v_fma_f32 v234, v164, v168, 0
	v_fma_f32 v235, v164, v169, 0
	v_fma_f32 v236, v164, v170, 0
	v_fma_f32 v237, v164, v171, 0
	v_fmac_f32_e32 v234, v165, v172
	v_fmac_f32_e32 v235, v165, v173
	v_fmac_f32_e32 v236, v165, v174
	v_fmac_f32_e32 v237, v165, v175
	v_fmac_f32_e32 v234, v166, v176
	v_fmac_f32_e32 v235, v166, v177
	v_fmac_f32_e32 v236, v166, v178
	v_fmac_f32_e32 v237, v166, v179
	v_fmac_f32_e32 v234, v167, v180
	v_fmac_f32_e32 v235, v167, v181
	v_fmac_f32_e32 v236, v167, v182
	v_fmac_f32_e32 v237, v167, v183
	ds_write_b128 v247, v[234:237] offset:0
	s_add_i32 s0, s7, 2
	s_cmp_gt_i32 s0, s4
	s_cbranch_scc1 .Lsc_x1_2
	s_waitcnt vmcnt(2)
	v_mfma_f32_16x16x32_bf16 v[168:171], v[48:51], v[0:3], 0
	v_mfma_f32_16x16x32_bf16 v[172:175], v[48:51], v[8:11], 0
	v_mfma_f32_16x16x32_bf16 v[176:179], v[48:51], v[16:19], 0
	v_mfma_f32_16x16x32_bf16 v[180:183], v[48:51], v[24:27], 0
	v_mfma_f32_16x16x32_bf16 v[168:171], v[52:55], v[4:7], v[168:171]
	v_mfma_f32_16x16x32_bf16 v[172:175], v[52:55], v[12:15], v[172:175]
	v_mfma_f32_16x16x32_bf16 v[176:179], v[52:55], v[20:23], v[176:179]
	v_mfma_f32_16x16x32_bf16 v[180:183], v[52:55], v[28:31], v[180:183]
	v_max_f32_e32 v184, 0, v184
	v_max_f32_e32 v185, 0, v185
	v_max_f32_e32 v186, 0, v186
	v_max_f32_e32 v187, 0, v187
	v_max_f32_e32 v188, 0, v188
	v_max_f32_e32 v189, 0, v189
	v_max_f32_e32 v190, 0, v190
	v_max_f32_e32 v191, 0, v191
	v_max_f32_e32 v226, 0, v226
	v_max_f32_e32 v227, 0, v227
	v_max_f32_e32 v228, 0, v228
	v_max_f32_e32 v229, 0, v229
	v_max_f32_e32 v230, 0, v230
	v_max_f32_e32 v231, 0, v231
	v_max_f32_e32 v232, 0, v232
	v_max_f32_e32 v233, 0, v233
	v_fma_f32 v238, v164, v184, 0
	v_fma_f32 v239, v164, v185, 0
	v_fma_f32 v240, v164, v186, 0
	v_fma_f32 v241, v164, v187, 0
	v_fmac_f32_e32 v238, v165, v188
	v_fmac_f32_e32 v239, v165, v189
	v_fmac_f32_e32 v240, v165, v190
	v_fmac_f32_e32 v241, v165, v191
	v_fmac_f32_e32 v238, v166, v226
	v_fmac_f32_e32 v239, v166, v227
	v_fmac_f32_e32 v240, v166, v228
	v_fmac_f32_e32 v241, v166, v229
	v_fmac_f32_e32 v238, v167, v230
	v_fmac_f32_e32 v239, v167, v231
	v_fmac_f32_e32 v240, v167, v232
	v_fmac_f32_e32 v241, v167, v233
	ds_write_b128 v247, v[238:241] offset:64
	s_add_i32 s0, s7, 3
	s_cmp_gt_i32 s0, s4
	s_cbranch_scc1 .Lsc_x1_3
	s_waitcnt vmcnt(0)
	v_mfma_f32_16x16x32_bf16 v[184:187], v[56:59], v[0:3], 0
	v_mfma_f32_16x16x32_bf16 v[188:191], v[56:59], v[8:11], 0
	v_mfma_f32_16x16x32_bf16 v[226:229], v[56:59], v[16:19], 0
	v_mfma_f32_16x16x32_bf16 v[230:233], v[56:59], v[24:27], 0
	v_mfma_f32_16x16x32_bf16 v[184:187], v[60:63], v[4:7], v[184:187]
	v_mfma_f32_16x16x32_bf16 v[188:191], v[60:63], v[12:15], v[188:191]
	v_mfma_f32_16x16x32_bf16 v[226:229], v[60:63], v[20:23], v[226:229]
	v_mfma_f32_16x16x32_bf16 v[230:233], v[60:63], v[28:31], v[230:233]
	v_max_f32_e32 v168, 0, v168
	v_max_f32_e32 v169, 0, v169
	v_max_f32_e32 v170, 0, v170
	v_max_f32_e32 v171, 0, v171
	v_max_f32_e32 v172, 0, v172
	v_max_f32_e32 v173, 0, v173
	v_max_f32_e32 v174, 0, v174
	v_max_f32_e32 v175, 0, v175
	v_max_f32_e32 v176, 0, v176
	v_max_f32_e32 v177, 0, v177
	v_max_f32_e32 v178, 0, v178
	v_max_f32_e32 v179, 0, v179
	v_max_f32_e32 v180, 0, v180
	v_max_f32_e32 v181, 0, v181
	v_max_f32_e32 v182, 0, v182
	v_max_f32_e32 v183, 0, v183
	v_fma_f32 v234, v164, v168, 0
	v_fma_f32 v235, v164, v169, 0
	v_fma_f32 v236, v164, v170, 0
	v_fma_f32 v237, v164, v171, 0
	v_fmac_f32_e32 v234, v165, v172
	v_fmac_f32_e32 v235, v165, v173
	v_fmac_f32_e32 v236, v165, v174
	v_fmac_f32_e32 v237, v165, v175
	v_fmac_f32_e32 v234, v166, v176
	v_fmac_f32_e32 v235, v166, v177
	v_fmac_f32_e32 v236, v166, v178
	v_fmac_f32_e32 v237, v166, v179
	v_fmac_f32_e32 v234, v167, v180
	v_fmac_f32_e32 v235, v167, v181
	v_fmac_f32_e32 v236, v167, v182
	v_fmac_f32_e32 v237, v167, v183
	ds_write_b128 v247, v[234:237] offset:128
	v_max_f32_e32 v184, 0, v184
	v_max_f32_e32 v185, 0, v185
	v_max_f32_e32 v186, 0, v186
	v_max_f32_e32 v187, 0, v187
	v_max_f32_e32 v188, 0, v188
	v_max_f32_e32 v189, 0, v189
	v_max_f32_e32 v190, 0, v190
	v_max_f32_e32 v191, 0, v191
	v_max_f32_e32 v226, 0, v226
	v_max_f32_e32 v227, 0, v227
	v_max_f32_e32 v228, 0, v228
	v_max_f32_e32 v229, 0, v229
	v_max_f32_e32 v230, 0, v230
	v_max_f32_e32 v231, 0, v231
	v_max_f32_e32 v232, 0, v232
	v_max_f32_e32 v233, 0, v233
	v_fma_f32 v238, v164, v184, 0
	v_fma_f32 v239, v164, v185, 0
	v_fma_f32 v240, v164, v186, 0
	v_fma_f32 v241, v164, v187, 0
	v_fmac_f32_e32 v238, v165, v188
	v_fmac_f32_e32 v239, v165, v189
	v_fmac_f32_e32 v240, v165, v190
	v_fmac_f32_e32 v241, v165, v191
	v_fmac_f32_e32 v238, v166, v226
	v_fmac_f32_e32 v239, v166, v227
	v_fmac_f32_e32 v240, v166, v228
	v_fmac_f32_e32 v241, v166, v229
	v_fmac_f32_e32 v238, v167, v230
	v_fmac_f32_e32 v239, v167, v231
	v_fmac_f32_e32 v240, v167, v232
	v_fmac_f32_e32 v241, v167, v233
	ds_write_b128 v247, v[238:241] offset:192
	s_branch .LBB0_820
.Lsc_x1_1:
	s_nop 9
	v_max_f32_e32 v168, 0, v168
	v_max_f32_e32 v169, 0, v169
	v_max_f32_e32 v170, 0, v170
	v_max_f32_e32 v171, 0, v171
	v_max_f32_e32 v172, 0, v172
	v_max_f32_e32 v173, 0, v173
	v_max_f32_e32 v174, 0, v174
	v_max_f32_e32 v175, 0, v175
	v_max_f32_e32 v176, 0, v176
	v_max_f32_e32 v177, 0, v177
	v_max_f32_e32 v178, 0, v178
	v_max_f32_e32 v179, 0, v179
	v_max_f32_e32 v180, 0, v180
	v_max_f32_e32 v181, 0, v181
	v_max_f32_e32 v182, 0, v182
	v_max_f32_e32 v183, 0, v183
	v_fma_f32 v234, v164, v168, 0
	v_fma_f32 v235, v164, v169, 0
	v_fma_f32 v236, v164, v170, 0
	v_fma_f32 v237, v164, v171, 0
	v_fmac_f32_e32 v234, v165, v172
	v_fmac_f32_e32 v235, v165, v173
	v_fmac_f32_e32 v236, v165, v174
	v_fmac_f32_e32 v237, v165, v175
	v_fmac_f32_e32 v234, v166, v176
	v_fmac_f32_e32 v235, v166, v177
	v_fmac_f32_e32 v236, v166, v178
	v_fmac_f32_e32 v237, v166, v179
	v_fmac_f32_e32 v234, v167, v180
	v_fmac_f32_e32 v235, v167, v181
	v_fmac_f32_e32 v236, v167, v182
	v_fmac_f32_e32 v237, v167, v183
	ds_write_b128 v247, v[234:237] offset:0
	s_branch .LBB0_820
.Lsc_x1_2:
	s_nop 9
	v_max_f32_e32 v184, 0, v184
	v_max_f32_e32 v185, 0, v185
	v_max_f32_e32 v186, 0, v186
	v_max_f32_e32 v187, 0, v187
	v_max_f32_e32 v188, 0, v188
	v_max_f32_e32 v189, 0, v189
	v_max_f32_e32 v190, 0, v190
	v_max_f32_e32 v191, 0, v191
	v_max_f32_e32 v226, 0, v226
	v_max_f32_e32 v227, 0, v227
	v_max_f32_e32 v228, 0, v228
	v_max_f32_e32 v229, 0, v229
	v_max_f32_e32 v230, 0, v230
	v_max_f32_e32 v231, 0, v231
	v_max_f32_e32 v232, 0, v232
	v_max_f32_e32 v233, 0, v233
	v_fma_f32 v238, v164, v184, 0
	v_fma_f32 v239, v164, v185, 0
	v_fma_f32 v240, v164, v186, 0
	v_fma_f32 v241, v164, v187, 0
	v_fmac_f32_e32 v238, v165, v188
	v_fmac_f32_e32 v239, v165, v189
	v_fmac_f32_e32 v240, v165, v190
	v_fmac_f32_e32 v241, v165, v191
	v_fmac_f32_e32 v238, v166, v226
	v_fmac_f32_e32 v239, v166, v227
	v_fmac_f32_e32 v240, v166, v228
	v_fmac_f32_e32 v241, v166, v229
	v_fmac_f32_e32 v238, v167, v230
	v_fmac_f32_e32 v239, v167, v231
	v_fmac_f32_e32 v240, v167, v232
	v_fmac_f32_e32 v241, v167, v233
	ds_write_b128 v247, v[238:241] offset:64
	s_branch .LBB0_820
.Lsc_x1_3:
	s_nop 9
	v_max_f32_e32 v168, 0, v168
	v_max_f32_e32 v169, 0, v169
	v_max_f32_e32 v170, 0, v170
	v_max_f32_e32 v171, 0, v171
	v_max_f32_e32 v172, 0, v172
	v_max_f32_e32 v173, 0, v173
	v_max_f32_e32 v174, 0, v174
	v_max_f32_e32 v175, 0, v175
	v_max_f32_e32 v176, 0, v176
	v_max_f32_e32 v177, 0, v177
	v_max_f32_e32 v178, 0, v178
	v_max_f32_e32 v179, 0, v179
	v_max_f32_e32 v180, 0, v180
	v_max_f32_e32 v181, 0, v181
	v_max_f32_e32 v182, 0, v182
	v_max_f32_e32 v183, 0, v183
	v_fma_f32 v234, v164, v168, 0
	v_fma_f32 v235, v164, v169, 0
	v_fma_f32 v236, v164, v170, 0
	v_fma_f32 v237, v164, v171, 0
	v_fmac_f32_e32 v234, v165, v172
	v_fmac_f32_e32 v235, v165, v173
	v_fmac_f32_e32 v236, v165, v174
	v_fmac_f32_e32 v237, v165, v175
	v_fmac_f32_e32 v234, v166, v176
	v_fmac_f32_e32 v235, v166, v177
	v_fmac_f32_e32 v236, v166, v178
	v_fmac_f32_e32 v237, v166, v179
	v_fmac_f32_e32 v234, v167, v180
	v_fmac_f32_e32 v235, v167, v181
	v_fmac_f32_e32 v236, v167, v182
	v_fmac_f32_e32 v237, v167, v183
	ds_write_b128 v247, v[234:237] offset:128
	s_branch .LBB0_820
.Lsc_g2:
	global_load_dwordx4 v[32:35], v245, s[42:43]
	global_load_dwordx4 v[36:39], v245, s[42:43] offset:64
	global_load_dwordx4 v[40:43], v245, s[42:43] offset:2048
	global_load_dwordx4 v[44:47], v245, s[42:43] offset:2112
	global_load_dwordx4 v[48:51], v246, s[42:43]
	global_load_dwordx4 v[52:55], v246, s[42:43] offset:64
	global_load_dwordx4 v[56:59], v246, s[42:43] offset:2048
	global_load_dwordx4 v[60:63], v246, s[42:43] offset:2112
	v_add_u32_e32 v245, 0x10000, v245
	v_add_u32_e32 v246, 0x10000, v246
	global_load_dwordx4 v[64:67], v245, s[42:43]
	global_load_dwordx4 v[68:71], v245, s[42:43] offset:64
	global_load_dwordx4 v[72:75], v245, s[42:43] offset:2048
	global_load_dwordx4 v[76:79], v245, s[42:43] offset:2112
	global_load_dwordx4 v[80:83], v246, s[42:43]
	global_load_dwordx4 v[84:87], v246, s[42:43] offset:64
	global_load_dwordx4 v[88:91], v246, s[42:43] offset:2048
	global_load_dwordx4 v[92:95], v246, s[42:43] offset:2112
	s_waitcnt vmcnt(14)
	v_mfma_f32_16x16x32_bf16 v[168:171], v[32:35], v[0:3], 0
	v_mfma_f32_16x16x32_bf16 v[172:175], v[32:35], v[8:11], 0
	v_mfma_f32_16x16x32_bf16 v[176:179], v[32:35], v[16:19], 0
	v_mfma_f32_16x16x32_bf16 v[180:183], v[32:35], v[24:27], 0
	v_mfma_f32_16x16x32_bf16 v[168:171], v[36:39], v[4:7], v[168:171]
	v_mfma_f32_16x16x32_bf16 v[172:175], v[36:39], v[12:15], v[172:175]
	v_mfma_f32_16x16x32_bf16 v[176:179], v[36:39], v[20:23], v[176:179]
	v_mfma_f32_16x16x32_bf16 v[180:183], v[36:39], v[28:31], v[180:183]
	s_waitcnt vmcnt(12)
	v_mfma_f32_16x16x32_bf16 v[184:187], v[40:43], v[0:3], 0
	v_mfma_f32_16x16x32_bf16 v[188:191], v[40:43], v[8:11], 0
	v_mfma_f32_16x16x32_bf16 v[226:229], v[40:43], v[16:19], 0
	v_mfma_f32_16x16x32_bf16 v[230:233], v[40:43], v[24:27], 0
	v_mfma_f32_16x16x32_bf16 v[184:187], v[44:47], v[4:7], v[184:187]
	v_mfma_f32_16x16x32_bf16 v[188:191], v[44:47], v[12:15], v[188:191]
	v_mfma_f32_16x16x32_bf16 v[226:229], v[44:47], v[20:23], v[226:229]
	v_mfma_f32_16x16x32_bf16 v[230:233], v[44:47], v[28:31], v[230:233]
	v_max_f32_e32 v168, 0, v168
	v_max_f32_e32 v169, 0, v169
	v_max_f32_e32 v170, 0, v170
	v_max_f32_e32 v171, 0, v171
	v_max_f32_e32 v172, 0, v172
	v_max_f32_e32 v173, 0, v173
	v_max_f32_e32 v174, 0, v174
	v_max_f32_e32 v175, 0, v175
	v_max_f32_e32 v176, 0, v176
	v_max_f32_e32 v177, 0, v177
	v_max_f32_e32 v178, 0, v178
	v_max_f32_e32 v179, 0, v179
	v_max_f32_e32 v180, 0, v180
	v_max_f32_e32 v181, 0, v181
	v_max_f32_e32 v182, 0, v182
	v_max_f32_e32 v183, 0, v183
	v_fma_f32 v234, v164, v168, 0
	v_fma_f32 v235, v164, v169, 0
	v_fma_f32 v236, v164, v170, 0
	v_fma_f32 v237, v164, v171, 0
	v_fmac_f32_e32 v234, v165, v172
	v_fmac_f32_e32 v235, v165, v173
	v_fmac_f32_e32 v236, v165, v174
	v_fmac_f32_e32 v237, v165, v175
	v_fmac_f32_e32 v234, v166, v176
	v_fmac_f32_e32 v235, v166, v177
	v_fmac_f32_e32 v236, v166, v178
	v_fmac_f32_e32 v237, v166, v179
	v_fmac_f32_e32 v234, v167, v180
	v_fmac_f32_e32 v235, v167, v181
	v_fmac_f32_e32 v236, v167, v182
	v_fmac_f32_e32 v237, v167, v183
	ds_write_b128 v247, v[234:237] offset:0
	s_waitcnt vmcnt(10)
	v_mfma_f32_16x16x32_bf16 v[168:171], v[48:51], v[0:3], 0
	v_mfma_f32_16x16x32_bf16 v[172:175], v[48:51], v[8:11], 0
	v_mfma_f32_16x16x32_bf16 v[176:179], v[48:51], v[16:19], 0
	v_mfma_f32_16x16x32_bf16 v[180:183], v[48:51], v[24:27], 0
	v_mfma_f32_16x16x32_bf16 v[168:171], v[52:55], v[4:7], v[168:171]
	v_mfma_f32_16x16x32_bf16 v[172:175], v[52:55], v[12:15], v[172:175]
	v_mfma_f32_16x16x32_bf16 v[176:179], v[52:55], v[20:23], v[176:179]
	v_mfma_f32_16x16x32_bf16 v[180:183], v[52:55], v[28:31], v[180:183]
	v_max_f32_e32 v184, 0, v184
	v_max_f32_e32 v185, 0, v185
	v_max_f32_e32 v186, 0, v186
	v_max_f32_e32 v187, 0, v187
	v_max_f32_e32 v188, 0, v188
	v_max_f32_e32 v189, 0, v189
	v_max_f32_e32 v190, 0, v190
	v_max_f32_e32 v191, 0, v191
	v_max_f32_e32 v226, 0, v226
	v_max_f32_e32 v227, 0, v227
	v_max_f32_e32 v228, 0, v228
	v_max_f32_e32 v229, 0, v229
	v_max_f32_e32 v230, 0, v230
	v_max_f32_e32 v231, 0, v231
	v_max_f32_e32 v232, 0, v232
	v_max_f32_e32 v233, 0, v233
	v_fma_f32 v238, v164, v184, 0
	v_fma_f32 v239, v164, v185, 0
	v_fma_f32 v240, v164, v186, 0
	v_fma_f32 v241, v164, v187, 0
	v_fmac_f32_e32 v238, v165, v188
	v_fmac_f32_e32 v239, v165, v189
	v_fmac_f32_e32 v240, v165, v190
	v_fmac_f32_e32 v241, v165, v191
	v_fmac_f32_e32 v238, v166, v226
	v_fmac_f32_e32 v239, v166, v227
	v_fmac_f32_e32 v240, v166, v228
	v_fmac_f32_e32 v241, v166, v229
	v_fmac_f32_e32 v238, v167, v230
	v_fmac_f32_e32 v239, v167, v231
	v_fmac_f32_e32 v240, v167, v232
	v_fmac_f32_e32 v241, v167, v233
	ds_write_b128 v247, v[238:241] offset:64
	s_waitcnt vmcnt(8)
	v_mfma_f32_16x16x32_bf16 v[184:187], v[56:59], v[0:3], 0
	v_mfma_f32_16x16x32_bf16 v[188:191], v[56:59], v[8:11], 0
	v_mfma_f32_16x16x32_bf16 v[226:229], v[56:59], v[16:19], 0
	v_mfma_f32_16x16x32_bf16 v[230:233], v[56:59], v[24:27], 0
	v_mfma_f32_16x16x32_bf16 v[184:187], v[60:63], v[4:7], v[184:187]
	v_mfma_f32_16x16x32_bf16 v[188:191], v[60:63], v[12:15], v[188:191]
	v_mfma_f32_16x16x32_bf16 v[226:229], v[60:63], v[20:23], v[226:229]
	v_mfma_f32_16x16x32_bf16 v[230:233], v[60:63], v[28:31], v[230:233]
	v_max_f32_e32 v168, 0, v168
	v_max_f32_e32 v169, 0, v169
	v_max_f32_e32 v170, 0, v170
	v_max_f32_e32 v171, 0, v171
	v_max_f32_e32 v172, 0, v172
	v_max_f32_e32 v173, 0, v173
	v_max_f32_e32 v174, 0, v174
	v_max_f32_e32 v175, 0, v175
	v_max_f32_e32 v176, 0, v176
	v_max_f32_e32 v177, 0, v177
	v_max_f32_e32 v178, 0, v178
	v_max_f32_e32 v179, 0, v179
	v_max_f32_e32 v180, 0, v180
	v_max_f32_e32 v181, 0, v181
	v_max_f32_e32 v182, 0, v182
	v_max_f32_e32 v183, 0, v183
	v_fma_f32 v234, v164, v168, 0
	v_fma_f32 v235, v164, v169, 0
	v_fma_f32 v236, v164, v170, 0
	v_fma_f32 v237, v164, v171, 0
	v_fmac_f32_e32 v234, v165, v172
	v_fmac_f32_e32 v235, v165, v173
	v_fmac_f32_e32 v236, v165, v174
	v_fmac_f32_e32 v237, v165, v175
	v_fmac_f32_e32 v234, v166, v176
	v_fmac_f32_e32 v235, v166, v177
	v_fmac_f32_e32 v236, v166, v178
	v_fmac_f32_e32 v237, v166, v179
	v_fmac_f32_e32 v234, v167, v180
	v_fmac_f32_e32 v235, v167, v181
	v_fmac_f32_e32 v236, v167, v182
	v_fmac_f32_e32 v237, v167, v183
	ds_write_b128 v247, v[234:237] offset:128
	s_waitcnt vmcnt(6)
	v_mfma_f32_16x16x32_bf16 v[168:171], v[64:67], v[0:3], 0
	v_mfma_f32_16x16x32_bf16 v[172:175], v[64:67], v[8:11], 0
	v_mfma_f32_16x16x32_bf16 v[176:179], v[64:67], v[16:19], 0
	v_mfma_f32_16x16x32_bf16 v[180:183], v[64:67], v[24:27], 0
	v_mfma_f32_16x16x32_bf16 v[168:171], v[68:71], v[4:7], v[168:171]
	v_mfma_f32_16x16x32_bf16 v[172:175], v[68:71], v[12:15], v[172:175]
	v_mfma_f32_16x16x32_bf16 v[176:179], v[68:71], v[20:23], v[176:179]
	v_mfma_f32_16x16x32_bf16 v[180:183], v[68:71], v[28:31], v[180:183]
	v_max_f32_e32 v184, 0, v184
	v_max_f32_e32 v185, 0, v185
	v_max_f32_e32 v186, 0, v186
	v_max_f32_e32 v187, 0, v187
	v_max_f32_e32 v188, 0, v188
	v_max_f32_e32 v189, 0, v189
	v_max_f32_e32 v190, 0, v190
	v_max_f32_e32 v191, 0, v191
	v_max_f32_e32 v226, 0, v226
	v_max_f32_e32 v227, 0, v227
	v_max_f32_e32 v228, 0, v228
	v_max_f32_e32 v229, 0, v229
	v_max_f32_e32 v230, 0, v230
	v_max_f32_e32 v231, 0, v231
	v_max_f32_e32 v232, 0, v232
	v_max_f32_e32 v233, 0, v233
	v_fma_f32 v238, v164, v184, 0
	v_fma_f32 v239, v164, v185, 0
	v_fma_f32 v240, v164, v186, 0
	v_fma_f32 v241, v164, v187, 0
	v_fmac_f32_e32 v238, v165, v188
	v_fmac_f32_e32 v239, v165, v189
	v_fmac_f32_e32 v240, v165, v190
	v_fmac_f32_e32 v241, v165, v191
	v_fmac_f32_e32 v238, v166, v226
	v_fmac_f32_e32 v239, v166, v227
	v_fmac_f32_e32 v240, v166, v228
	v_fmac_f32_e32 v241, v166, v229
	v_fmac_f32_e32 v238, v167, v230
	v_fmac_f32_e32 v239, v167, v231
	v_fmac_f32_e32 v240, v167, v232
	v_fmac_f32_e32 v241, v167, v233
	ds_write_b128 v247, v[238:241] offset:192
	s_add_i32 s0, s7, 33
	s_cmp_gt_i32 s0, s4
	s_cbranch_scc1 .Lsc_x2_5
	s_waitcnt vmcnt(4)
	v_mfma_f32_16x16x32_bf16 v[184:187], v[72:75], v[0:3], 0
	v_mfma_f32_16x16x32_bf16 v[188:191], v[72:75], v[8:11], 0
	v_mfma_f32_16x16x32_bf16 v[226:229], v[72:75], v[16:19], 0
	v_mfma_f32_16x16x32_bf16 v[230:233], v[72:75], v[24:27], 0
	v_mfma_f32_16x16x32_bf16 v[184:187], v[76:79], v[4:7], v[184:187]
	v_mfma_f32_16x16x32_bf16 v[188:191], v[76:79], v[12:15], v[188:191]
	v_mfma_f32_16x16x32_bf16 v[226:229], v[76:79], v[20:23], v[226:229]
	v_mfma_f32_16x16x32_bf16 v[230:233], v[76:79], v[28:31], v[230:233]
	v_max_f32_e32 v168, 0, v168
	v_max_f32_e32 v169, 0, v169
	v_max_f32_e32 v170, 0, v170
	v_max_f32_e32 v171, 0, v171
	v_max_f32_e32 v172, 0, v172
	v_max_f32_e32 v173, 0, v173
	v_max_f32_e32 v174, 0, v174
	v_max_f32_e32 v175, 0, v175
	v_max_f32_e32 v176, 0, v176
	v_max_f32_e32 v177, 0, v177
	v_max_f32_e32 v178, 0, v178
	v_max_f32_e32 v179, 0, v179
	v_max_f32_e32 v180, 0, v180
	v_max_f32_e32 v181, 0, v181
	v_max_f32_e32 v182, 0, v182
	v_max_f32_e32 v183, 0, v183
	v_fma_f32 v234, v164, v168, 0
	v_fma_f32 v235, v164, v169, 0
	v_fma_f32 v236, v164, v170, 0
	v_fma_f32 v237, v164, v171, 0
	v_fmac_f32_e32 v234, v165, v172
	v_fmac_f32_e32 v235, v165, v173
	v_fmac_f32_e32 v236, v165, v174
	v_fmac_f32_e32 v237, v165, v175
	v_fmac_f32_e32 v234, v166, v176
	v_fmac_f32_e32 v235, v166, v177
	v_fmac_f32_e32 v236, v166, v178
	v_fmac_f32_e32 v237, v166, v179
	v_fmac_f32_e32 v234, v167, v180
	v_fmac_f32_e32 v235, v167, v181
	v_fmac_f32_e32 v236, v167, v182
	v_fmac_f32_e32 v237, v167, v183
	ds_write_b128 v247, v[234:237] offset:2048
	s_add_i32 s0, s7, 34
	s_cmp_gt_i32 s0, s4
	s_cbranch_scc1 .Lsc_x2_6
	s_waitcnt vmcnt(2)
	v_mfma_f32_16x16x32_bf16 v[168:171], v[80:83], v[0:3], 0
	v_mfma_f32_16x16x32_bf16 v[172:175], v[80:83], v[8:11], 0
	v_mfma_f32_16x16x32_bf16 v[176:179], v[80:83], v[16:19], 0
	v_mfma_f32_16x16x32_bf16 v[180:183], v[80:83], v[24:27], 0
	v_mfma_f32_16x16x32_bf16 v[168:171], v[84:87], v[4:7], v[168:171]
	v_mfma_f32_16x16x32_bf16 v[172:175], v[84:87], v[12:15], v[172:175]
	v_mfma_f32_16x16x32_bf16 v[176:179], v[84:87], v[20:23], v[176:179]
	v_mfma_f32_16x16x32_bf16 v[180:183], v[84:87], v[28:31], v[180:183]
	v_max_f32_e32 v184, 0, v184
	v_max_f32_e32 v185, 0, v185
	v_max_f32_e32 v186, 0, v186
	v_max_f32_e32 v187, 0, v187
	v_max_f32_e32 v188, 0, v188
	v_max_f32_e32 v189, 0, v189
	v_max_f32_e32 v190, 0, v190
	v_max_f32_e32 v191, 0, v191
	v_max_f32_e32 v226, 0, v226
	v_max_f32_e32 v227, 0, v227
	v_max_f32_e32 v228, 0, v228
	v_max_f32_e32 v229, 0, v229
	v_max_f32_e32 v230, 0, v230
	v_max_f32_e32 v231, 0, v231
	v_max_f32_e32 v232, 0, v232
	v_max_f32_e32 v233, 0, v233
	v_fma_f32 v238, v164, v184, 0
	v_fma_f32 v239, v164, v185, 0
	v_fma_f32 v240, v164, v186, 0
	v_fma_f32 v241, v164, v187, 0
	v_fmac_f32_e32 v238, v165, v188
	v_fmac_f32_e32 v239, v165, v189
	v_fmac_f32_e32 v240, v165, v190
	v_fmac_f32_e32 v241, v165, v191
	v_fmac_f32_e32 v238, v166, v226
	v_fmac_f32_e32 v239, v166, v227
	v_fmac_f32_e32 v240, v166, v228
	v_fmac_f32_e32 v241, v166, v229
	v_fmac_f32_e32 v238, v167, v230
	v_fmac_f32_e32 v239, v167, v231
	v_fmac_f32_e32 v240, v167, v232
	v_fmac_f32_e32 v241, v167, v233
	ds_write_b128 v247, v[238:241] offset:2112
	s_add_i32 s0, s7, 35
	s_cmp_gt_i32 s0, s4
	s_cbranch_scc1 .Lsc_x2_7
	s_waitcnt vmcnt(0)
	v_mfma_f32_16x16x32_bf16 v[184:187], v[88:91], v[0:3], 0
	v_mfma_f32_16x16x32_bf16 v[188:191], v[88:91], v[8:11], 0
	v_mfma_f32_16x16x32_bf16 v[226:229], v[88:91], v[16:19], 0
	v_mfma_f32_16x16x32_bf16 v[230:233], v[88:91], v[24:27], 0
	v_mfma_f32_16x16x32_bf16 v[184:187], v[92:95], v[4:7], v[184:187]
	v_mfma_f32_16x16x32_bf16 v[188:191], v[92:95], v[12:15], v[188:191]
	v_mfma_f32_16x16x32_bf16 v[226:229], v[92:95], v[20:23], v[226:229]
	v_mfma_f32_16x16x32_bf16 v[230:233], v[92:95], v[28:31], v[230:233]
	v_max_f32_e32 v168, 0, v168
	v_max_f32_e32 v169, 0, v169
	v_max_f32_e32 v170, 0, v170
	v_max_f32_e32 v171, 0, v171
	v_max_f32_e32 v172, 0, v172
	v_max_f32_e32 v173, 0, v173
	v_max_f32_e32 v174, 0, v174
	v_max_f32_e32 v175, 0, v175
	v_max_f32_e32 v176, 0, v176
	v_max_f32_e32 v177, 0, v177
	v_max_f32_e32 v178, 0, v178
	v_max_f32_e32 v179, 0, v179
	v_max_f32_e32 v180, 0, v180
	v_max_f32_e32 v181, 0, v181
	v_max_f32_e32 v182, 0, v182
	v_max_f32_e32 v183, 0, v183
	v_fma_f32 v234, v164, v168, 0
	v_fma_f32 v235, v164, v169, 0
	v_fma_f32 v236, v164, v170, 0
	v_fma_f32 v237, v164, v171, 0
	v_fmac_f32_e32 v234, v165, v172
	v_fmac_f32_e32 v235, v165, v173
	v_fmac_f32_e32 v236, v165, v174
	v_fmac_f32_e32 v237, v165, v175
	v_fmac_f32_e32 v234, v166, v176
	v_fmac_f32_e32 v235, v166, v177
	v_fmac_f32_e32 v236, v166, v178
	v_fmac_f32_e32 v237, v166, v179
	v_fmac_f32_e32 v234, v167, v180
	v_fmac_f32_e32 v235, v167, v181
	v_fmac_f32_e32 v236, v167, v182
	v_fmac_f32_e32 v237, v167, v183
	ds_write_b128 v247, v[234:237] offset:2176
	v_max_f32_e32 v184, 0, v184
	v_max_f32_e32 v185, 0, v185
	v_max_f32_e32 v186, 0, v186
	v_max_f32_e32 v187, 0, v187
	v_max_f32_e32 v188, 0, v188
	v_max_f32_e32 v189, 0, v189
	v_max_f32_e32 v190, 0, v190
	v_max_f32_e32 v191, 0, v191
	v_max_f32_e32 v226, 0, v226
	v_max_f32_e32 v227, 0, v227
	v_max_f32_e32 v228, 0, v228
	v_max_f32_e32 v229, 0, v229
	v_max_f32_e32 v230, 0, v230
	v_max_f32_e32 v231, 0, v231
	v_max_f32_e32 v232, 0, v232
	v_max_f32_e32 v233, 0, v233
	v_fma_f32 v238, v164, v184, 0
	v_fma_f32 v239, v164, v185, 0
	v_fma_f32 v240, v164, v186, 0
	v_fma_f32 v241, v164, v187, 0
	v_fmac_f32_e32 v238, v165, v188
	v_fmac_f32_e32 v239, v165, v189
	v_fmac_f32_e32 v240, v165, v190
	v_fmac_f32_e32 v241, v165, v191
	v_fmac_f32_e32 v238, v166, v226
	v_fmac_f32_e32 v239, v166, v227
	v_fmac_f32_e32 v240, v166, v228
	v_fmac_f32_e32 v241, v166, v229
	v_fmac_f32_e32 v238, v167, v230
	v_fmac_f32_e32 v239, v167, v231
	v_fmac_f32_e32 v240, v167, v232
	v_fmac_f32_e32 v241, v167, v233
	ds_write_b128 v247, v[238:241] offset:2240
	s_branch .LBB0_820
.Lsc_x2_5:
	s_nop 9
	v_max_f32_e32 v168, 0, v168
	v_max_f32_e32 v169, 0, v169
	v_max_f32_e32 v170, 0, v170
	v_max_f32_e32 v171, 0, v171
	v_max_f32_e32 v172, 0, v172
	v_max_f32_e32 v173, 0, v173
	v_max_f32_e32 v174, 0, v174
	v_max_f32_e32 v175, 0, v175
	v_max_f32_e32 v176, 0, v176
	v_max_f32_e32 v177, 0, v177
	v_max_f32_e32 v178, 0, v178
	v_max_f32_e32 v179, 0, v179
	v_max_f32_e32 v180, 0, v180
	v_max_f32_e32 v181, 0, v181
	v_max_f32_e32 v182, 0, v182
	v_max_f32_e32 v183, 0, v183
	v_fma_f32 v234, v164, v168, 0
	v_fma_f32 v235, v164, v169, 0
	v_fma_f32 v236, v164, v170, 0
	v_fma_f32 v237, v164, v171, 0
	v_fmac_f32_e32 v234, v165, v172
	v_fmac_f32_e32 v235, v165, v173
	v_fmac_f32_e32 v236, v165, v174
	v_fmac_f32_e32 v237, v165, v175
	v_fmac_f32_e32 v234, v166, v176
	v_fmac_f32_e32 v235, v166, v177
	v_fmac_f32_e32 v236, v166, v178
	v_fmac_f32_e32 v237, v166, v179
	v_fmac_f32_e32 v234, v167, v180
	v_fmac_f32_e32 v235, v167, v181
	v_fmac_f32_e32 v236, v167, v182
	v_fmac_f32_e32 v237, v167, v183
	ds_write_b128 v247, v[234:237] offset:2048
	s_branch .LBB0_820
.Lsc_x2_6:
	s_nop 9
	v_max_f32_e32 v184, 0, v184
	v_max_f32_e32 v185, 0, v185
	v_max_f32_e32 v186, 0, v186
	v_max_f32_e32 v187, 0, v187
	v_max_f32_e32 v188, 0, v188
	v_max_f32_e32 v189, 0, v189
	v_max_f32_e32 v190, 0, v190
	v_max_f32_e32 v191, 0, v191
	v_max_f32_e32 v226, 0, v226
	v_max_f32_e32 v227, 0, v227
	v_max_f32_e32 v228, 0, v228
	v_max_f32_e32 v229, 0, v229
	v_max_f32_e32 v230, 0, v230
	v_max_f32_e32 v231, 0, v231
	v_max_f32_e32 v232, 0, v232
	v_max_f32_e32 v233, 0, v233
	v_fma_f32 v238, v164, v184, 0
	v_fma_f32 v239, v164, v185, 0
	v_fma_f32 v240, v164, v186, 0
	v_fma_f32 v241, v164, v187, 0
	v_fmac_f32_e32 v238, v165, v188
	v_fmac_f32_e32 v239, v165, v189
	v_fmac_f32_e32 v240, v165, v190
	v_fmac_f32_e32 v241, v165, v191
	v_fmac_f32_e32 v238, v166, v226
	v_fmac_f32_e32 v239, v166, v227
	v_fmac_f32_e32 v240, v166, v228
	v_fmac_f32_e32 v241, v166, v229
	v_fmac_f32_e32 v238, v167, v230
	v_fmac_f32_e32 v239, v167, v231
	v_fmac_f32_e32 v240, v167, v232
	v_fmac_f32_e32 v241, v167, v233
	ds_write_b128 v247, v[238:241] offset:2112
	s_branch .LBB0_820
.Lsc_x2_7:
	s_nop 9
	v_max_f32_e32 v168, 0, v168
	v_max_f32_e32 v169, 0, v169
	v_max_f32_e32 v170, 0, v170
	v_max_f32_e32 v171, 0, v171
	v_max_f32_e32 v172, 0, v172
	v_max_f32_e32 v173, 0, v173
	v_max_f32_e32 v174, 0, v174
	v_max_f32_e32 v175, 0, v175
	v_max_f32_e32 v176, 0, v176
	v_max_f32_e32 v177, 0, v177
	v_max_f32_e32 v178, 0, v178
	v_max_f32_e32 v179, 0, v179
	v_max_f32_e32 v180, 0, v180
	v_max_f32_e32 v181, 0, v181
	v_max_f32_e32 v182, 0, v182
	v_max_f32_e32 v183, 0, v183
	v_fma_f32 v234, v164, v168, 0
	v_fma_f32 v235, v164, v169, 0
	v_fma_f32 v236, v164, v170, 0
	v_fma_f32 v237, v164, v171, 0
	v_fmac_f32_e32 v234, v165, v172
	v_fmac_f32_e32 v235, v165, v173
	v_fmac_f32_e32 v236, v165, v174
	v_fmac_f32_e32 v237, v165, v175
	v_fmac_f32_e32 v234, v166, v176
	v_fmac_f32_e32 v235, v166, v177
	v_fmac_f32_e32 v236, v166, v178
	v_fmac_f32_e32 v237, v166, v179
	v_fmac_f32_e32 v234, v167, v180
	v_fmac_f32_e32 v235, v167, v181
	v_fmac_f32_e32 v236, v167, v182
	v_fmac_f32_e32 v237, v167, v183
	ds_write_b128 v247, v[234:237] offset:2176
	s_branch .LBB0_820
.Lsc_g3:
	global_load_dwordx4 v[32:35], v245, s[42:43]
	global_load_dwordx4 v[36:39], v245, s[42:43] offset:64
	global_load_dwordx4 v[40:43], v245, s[42:43] offset:2048
	global_load_dwordx4 v[44:47], v245, s[42:43] offset:2112
	global_load_dwordx4 v[48:51], v246, s[42:43]
	global_load_dwordx4 v[52:55], v246, s[42:43] offset:64
	global_load_dwordx4 v[56:59], v246, s[42:43] offset:2048
	global_load_dwordx4 v[60:63], v246, s[42:43] offset:2112
	v_add_u32_e32 v245, 0x10000, v245
	v_add_u32_e32 v246, 0x10000, v246
	global_load_dwordx4 v[64:67], v245, s[42:43]
	global_load_dwordx4 v[68:71], v245, s[42:43] offset:64
	global_load_dwordx4 v[72:75], v245, s[42:43] offset:2048
	global_load_dwordx4 v[76:79], v245, s[42:43] offset:2112
	global_load_dwordx4 v[80:83], v246, s[42:43]
	global_load_dwordx4 v[84:87], v246, s[42:43] offset:64
	global_load_dwordx4 v[88:91], v246, s[42:43] offset:2048
	global_load_dwordx4 v[92:95], v246, s[42:43] offset:2112
	v_add_u32_e32 v245, 0x10000, v245
	v_add_u32_e32 v246, 0x10000, v246
	global_load_dwordx4 v[96:99], v245, s[42:43]
	global_load_dwordx4 v[100:103], v245, s[42:43] offset:64
	global_load_dwordx4 v[104:107], v245, s[42:43] offset:2048
	global_load_dwordx4 v[108:111], v245, s[42:43] offset:2112
	global_load_dwordx4 v[112:115], v246, s[42:43]
	global_load_dwordx4 v[116:119], v246, s[42:43] offset:64
	global_load_dwordx4 v[120:123], v246, s[42:43] offset:2048
	global_load_dwordx4 v[124:127], v246, s[42:43] offset:2112
	s_waitcnt vmcnt(22)
	v_mfma_f32_16x16x32_bf16 v[168:171], v[32:35], v[0:3], 0
	v_mfma_f32_16x16x32_bf16 v[172:175], v[32:35], v[8:11], 0
	v_mfma_f32_16x16x32_bf16 v[176:179], v[32:35], v[16:19], 0
	v_mfma_f32_16x16x32_bf16 v[180:183], v[32:35], v[24:27], 0
	v_mfma_f32_16x16x32_bf16 v[168:171], v[36:39], v[4:7], v[168:171]
	v_mfma_f32_16x16x32_bf16 v[172:175], v[36:39], v[12:15], v[172:175]
	v_mfma_f32_16x16x32_bf16 v[176:179], v[36:39], v[20:23], v[176:179]
	v_mfma_f32_16x16x32_bf16 v[180:183], v[36:39], v[28:31], v[180:183]
	s_waitcnt vmcnt(20)
	v_mfma_f32_16x16x32_bf16 v[184:187], v[40:43], v[0:3], 0
	v_mfma_f32_16x16x32_bf16 v[188:191], v[40:43], v[8:11], 0
	v_mfma_f32_16x16x32_bf16 v[226:229], v[40:43], v[16:19], 0
	v_mfma_f32_16x16x32_bf16 v[230:233], v[40:43], v[24:27], 0
	v_mfma_f32_16x16x32_bf16 v[184:187], v[44:47], v[4:7], v[184:187]
	v_mfma_f32_16x16x32_bf16 v[188:191], v[44:47], v[12:15], v[188:191]
	v_mfma_f32_16x16x32_bf16 v[226:229], v[44:47], v[20:23], v[226:229]
	v_mfma_f32_16x16x32_bf16 v[230:233], v[44:47], v[28:31], v[230:233]
	v_max_f32_e32 v168, 0, v168
	v_max_f32_e32 v169, 0, v169
	v_max_f32_e32 v170, 0, v170
	v_max_f32_e32 v171, 0, v171
	v_max_f32_e32 v172, 0, v172
	v_max_f32_e32 v173, 0, v173
	v_max_f32_e32 v174, 0, v174
	v_max_f32_e32 v175, 0, v175
	v_max_f32_e32 v176, 0, v176
	v_max_f32_e32 v177, 0, v177
	v_max_f32_e32 v178, 0, v178
	v_max_f32_e32 v179, 0, v179
	v_max_f32_e32 v180, 0, v180
	v_max_f32_e32 v181, 0, v181
	v_max_f32_e32 v182, 0, v182
	v_max_f32_e32 v183, 0, v183
	v_fma_f32 v234, v164, v168, 0
	v_fma_f32 v235, v164, v169, 0
	v_fma_f32 v236, v164, v170, 0
	v_fma_f32 v237, v164, v171, 0
	v_fmac_f32_e32 v234, v165, v172
	v_fmac_f32_e32 v235, v165, v173
	v_fmac_f32_e32 v236, v165, v174
	v_fmac_f32_e32 v237, v165, v175
	v_fmac_f32_e32 v234, v166, v176
	v_fmac_f32_e32 v235, v166, v177
	v_fmac_f32_e32 v236, v166, v178
	v_fmac_f32_e32 v237, v166, v179
	v_fmac_f32_e32 v234, v167, v180
	v_fmac_f32_e32 v235, v167, v181
	v_fmac_f32_e32 v236, v167, v182
	v_fmac_f32_e32 v237, v167, v183
	ds_write_b128 v247, v[234:237] offset:0
	s_waitcnt vmcnt(18)
	v_mfma_f32_16x16x32_bf16 v[168:171], v[48:51], v[0:3], 0
	v_mfma_f32_16x16x32_bf16 v[172:175], v[48:51], v[8:11], 0
	v_mfma_f32_16x16x32_bf16 v[176:179], v[48:51], v[16:19], 0
	v_mfma_f32_16x16x32_bf16 v[180:183], v[48:51], v[24:27], 0
	v_mfma_f32_16x16x32_bf16 v[168:171], v[52:55], v[4:7], v[168:171]
	v_mfma_f32_16x16x32_bf16 v[172:175], v[52:55], v[12:15], v[172:175]
	v_mfma_f32_16x16x32_bf16 v[176:179], v[52:55], v[20:23], v[176:179]
	v_mfma_f32_16x16x32_bf16 v[180:183], v[52:55], v[28:31], v[180:183]
	v_max_f32_e32 v184, 0, v184
	v_max_f32_e32 v185, 0, v185
	v_max_f32_e32 v186, 0, v186
	v_max_f32_e32 v187, 0, v187
	v_max_f32_e32 v188, 0, v188
	v_max_f32_e32 v189, 0, v189
	v_max_f32_e32 v190, 0, v190
	v_max_f32_e32 v191, 0, v191
	v_max_f32_e32 v226, 0, v226
	v_max_f32_e32 v227, 0, v227
	v_max_f32_e32 v228, 0, v228
	v_max_f32_e32 v229, 0, v229
	v_max_f32_e32 v230, 0, v230
	v_max_f32_e32 v231, 0, v231
	v_max_f32_e32 v232, 0, v232
	v_max_f32_e32 v233, 0, v233
	v_fma_f32 v238, v164, v184, 0
	v_fma_f32 v239, v164, v185, 0
	v_fma_f32 v240, v164, v186, 0
	v_fma_f32 v241, v164, v187, 0
	v_fmac_f32_e32 v238, v165, v188
	v_fmac_f32_e32 v239, v165, v189
	v_fmac_f32_e32 v240, v165, v190
	v_fmac_f32_e32 v241, v165, v191
	v_fmac_f32_e32 v238, v166, v226
	v_fmac_f32_e32 v239, v166, v227
	v_fmac_f32_e32 v240, v166, v228
	v_fmac_f32_e32 v241, v166, v229
	v_fmac_f32_e32 v238, v167, v230
	v_fmac_f32_e32 v239, v167, v231
	v_fmac_f32_e32 v240, v167, v232
	v_fmac_f32_e32 v241, v167, v233
	ds_write_b128 v247, v[238:241] offset:64
	s_waitcnt vmcnt(16)
	v_mfma_f32_16x16x32_bf16 v[184:187], v[56:59], v[0:3], 0
	v_mfma_f32_16x16x32_bf16 v[188:191], v[56:59], v[8:11], 0
	v_mfma_f32_16x16x32_bf16 v[226:229], v[56:59], v[16:19], 0
	v_mfma_f32_16x16x32_bf16 v[230:233], v[56:59], v[24:27], 0
	v_mfma_f32_16x16x32_bf16 v[184:187], v[60:63], v[4:7], v[184:187]
	v_mfma_f32_16x16x32_bf16 v[188:191], v[60:63], v[12:15], v[188:191]
	v_mfma_f32_16x16x32_bf16 v[226:229], v[60:63], v[20:23], v[226:229]
	v_mfma_f32_16x16x32_bf16 v[230:233], v[60:63], v[28:31], v[230:233]
	v_max_f32_e32 v168, 0, v168
	v_max_f32_e32 v169, 0, v169
	v_max_f32_e32 v170, 0, v170
	v_max_f32_e32 v171, 0, v171
	v_max_f32_e32 v172, 0, v172
	v_max_f32_e32 v173, 0, v173
	v_max_f32_e32 v174, 0, v174
	v_max_f32_e32 v175, 0, v175
	v_max_f32_e32 v176, 0, v176
	v_max_f32_e32 v177, 0, v177
	v_max_f32_e32 v178, 0, v178
	v_max_f32_e32 v179, 0, v179
	v_max_f32_e32 v180, 0, v180
	v_max_f32_e32 v181, 0, v181
	v_max_f32_e32 v182, 0, v182
	v_max_f32_e32 v183, 0, v183
	v_fma_f32 v234, v164, v168, 0
	v_fma_f32 v235, v164, v169, 0
	v_fma_f32 v236, v164, v170, 0
	v_fma_f32 v237, v164, v171, 0
	v_fmac_f32_e32 v234, v165, v172
	v_fmac_f32_e32 v235, v165, v173
	v_fmac_f32_e32 v236, v165, v174
	v_fmac_f32_e32 v237, v165, v175
	v_fmac_f32_e32 v234, v166, v176
	v_fmac_f32_e32 v235, v166, v177
	v_fmac_f32_e32 v236, v166, v178
	v_fmac_f32_e32 v237, v166, v179
	v_fmac_f32_e32 v234, v167, v180
	v_fmac_f32_e32 v235, v167, v181
	v_fmac_f32_e32 v236, v167, v182
	v_fmac_f32_e32 v237, v167, v183
	ds_write_b128 v247, v[234:237] offset:128
	s_waitcnt vmcnt(14)
	v_mfma_f32_16x16x32_bf16 v[168:171], v[64:67], v[0:3], 0
	v_mfma_f32_16x16x32_bf16 v[172:175], v[64:67], v[8:11], 0
	v_mfma_f32_16x16x32_bf16 v[176:179], v[64:67], v[16:19], 0
	v_mfma_f32_16x16x32_bf16 v[180:183], v[64:67], v[24:27], 0
	v_mfma_f32_16x16x32_bf16 v[168:171], v[68:71], v[4:7], v[168:171]
	v_mfma_f32_16x16x32_bf16 v[172:175], v[68:71], v[12:15], v[172:175]
	v_mfma_f32_16x16x32_bf16 v[176:179], v[68:71], v[20:23], v[176:179]
	v_mfma_f32_16x16x32_bf16 v[180:183], v[68:71], v[28:31], v[180:183]
	v_max_f32_e32 v184, 0, v184
	v_max_f32_e32 v185, 0, v185
	v_max_f32_e32 v186, 0, v186
	v_max_f32_e32 v187, 0, v187
	v_max_f32_e32 v188, 0, v188
	v_max_f32_e32 v189, 0, v189
	v_max_f32_e32 v190, 0, v190
	v_max_f32_e32 v191, 0, v191
	v_max_f32_e32 v226, 0, v226
	v_max_f32_e32 v227, 0, v227
	v_max_f32_e32 v228, 0, v228
	v_max_f32_e32 v229, 0, v229
	v_max_f32_e32 v230, 0, v230
	v_max_f32_e32 v231, 0, v231
	v_max_f32_e32 v232, 0, v232
	v_max_f32_e32 v233, 0, v233
	v_fma_f32 v238, v164, v184, 0
	v_fma_f32 v239, v164, v185, 0
	v_fma_f32 v240, v164, v186, 0
	v_fma_f32 v241, v164, v187, 0
	v_fmac_f32_e32 v238, v165, v188
	v_fmac_f32_e32 v239, v165, v189
	v_fmac_f32_e32 v240, v165, v190
	v_fmac_f32_e32 v241, v165, v191
	v_fmac_f32_e32 v238, v166, v226
	v_fmac_f32_e32 v239, v166, v227
	v_fmac_f32_e32 v240, v166, v228
	v_fmac_f32_e32 v241, v166, v229
	v_fmac_f32_e32 v238, v167, v230
	v_fmac_f32_e32 v239, v167, v231
	v_fmac_f32_e32 v240, v167, v232
	v_fmac_f32_e32 v241, v167, v233
	ds_write_b128 v247, v[238:241] offset:192
	s_waitcnt vmcnt(12)
	v_mfma_f32_16x16x32_bf16 v[184:187], v[72:75], v[0:3], 0
	v_mfma_f32_16x16x32_bf16 v[188:191], v[72:75], v[8:11], 0
	v_mfma_f32_16x16x32_bf16 v[226:229], v[72:75], v[16:19], 0
	v_mfma_f32_16x16x32_bf16 v[230:233], v[72:75], v[24:27], 0
	v_mfma_f32_16x16x32_bf16 v[184:187], v[76:79], v[4:7], v[184:187]
	v_mfma_f32_16x16x32_bf16 v[188:191], v[76:79], v[12:15], v[188:191]
	v_mfma_f32_16x16x32_bf16 v[226:229], v[76:79], v[20:23], v[226:229]
	v_mfma_f32_16x16x32_bf16 v[230:233], v[76:79], v[28:31], v[230:233]
	v_max_f32_e32 v168, 0, v168
	v_max_f32_e32 v169, 0, v169
	v_max_f32_e32 v170, 0, v170
	v_max_f32_e32 v171, 0, v171
	v_max_f32_e32 v172, 0, v172
	v_max_f32_e32 v173, 0, v173
	v_max_f32_e32 v174, 0, v174
	v_max_f32_e32 v175, 0, v175
	v_max_f32_e32 v176, 0, v176
	v_max_f32_e32 v177, 0, v177
	v_max_f32_e32 v178, 0, v178
	v_max_f32_e32 v179, 0, v179
	v_max_f32_e32 v180, 0, v180
	v_max_f32_e32 v181, 0, v181
	v_max_f32_e32 v182, 0, v182
	v_max_f32_e32 v183, 0, v183
	v_fma_f32 v234, v164, v168, 0
	v_fma_f32 v235, v164, v169, 0
	v_fma_f32 v236, v164, v170, 0
	v_fma_f32 v237, v164, v171, 0
	v_fmac_f32_e32 v234, v165, v172
	v_fmac_f32_e32 v235, v165, v173
	v_fmac_f32_e32 v236, v165, v174
	v_fmac_f32_e32 v237, v165, v175
	v_fmac_f32_e32 v234, v166, v176
	v_fmac_f32_e32 v235, v166, v177
	v_fmac_f32_e32 v236, v166, v178
	v_fmac_f32_e32 v237, v166, v179
	v_fmac_f32_e32 v234, v167, v180
	v_fmac_f32_e32 v235, v167, v181
	v_fmac_f32_e32 v236, v167, v182
	v_fmac_f32_e32 v237, v167, v183
	ds_write_b128 v247, v[234:237] offset:2048
	s_waitcnt vmcnt(10)
	v_mfma_f32_16x16x32_bf16 v[168:171], v[80:83], v[0:3], 0
	v_mfma_f32_16x16x32_bf16 v[172:175], v[80:83], v[8:11], 0
	v_mfma_f32_16x16x32_bf16 v[176:179], v[80:83], v[16:19], 0
	v_mfma_f32_16x16x32_bf16 v[180:183], v[80:83], v[24:27], 0
	v_mfma_f32_16x16x32_bf16 v[168:171], v[84:87], v[4:7], v[168:171]
	v_mfma_f32_16x16x32_bf16 v[172:175], v[84:87], v[12:15], v[172:175]
	v_mfma_f32_16x16x32_bf16 v[176:179], v[84:87], v[20:23], v[176:179]
	v_mfma_f32_16x16x32_bf16 v[180:183], v[84:87], v[28:31], v[180:183]
	v_max_f32_e32 v184, 0, v184
	v_max_f32_e32 v185, 0, v185
	v_max_f32_e32 v186, 0, v186
	v_max_f32_e32 v187, 0, v187
	v_max_f32_e32 v188, 0, v188
	v_max_f32_e32 v189, 0, v189
	v_max_f32_e32 v190, 0, v190
	v_max_f32_e32 v191, 0, v191
	v_max_f32_e32 v226, 0, v226
	v_max_f32_e32 v227, 0, v227
	v_max_f32_e32 v228, 0, v228
	v_max_f32_e32 v229, 0, v229
	v_max_f32_e32 v230, 0, v230
	v_max_f32_e32 v231, 0, v231
	v_max_f32_e32 v232, 0, v232
	v_max_f32_e32 v233, 0, v233
	v_fma_f32 v238, v164, v184, 0
	v_fma_f32 v239, v164, v185, 0
	v_fma_f32 v240, v164, v186, 0
	v_fma_f32 v241, v164, v187, 0
	v_fmac_f32_e32 v238, v165, v188
	v_fmac_f32_e32 v239, v165, v189
	v_fmac_f32_e32 v240, v165, v190
	v_fmac_f32_e32 v241, v165, v191
	v_fmac_f32_e32 v238, v166, v226
	v_fmac_f32_e32 v239, v166, v227
	v_fmac_f32_e32 v240, v166, v228
	v_fmac_f32_e32 v241, v166, v229
	v_fmac_f32_e32 v238, v167, v230
	v_fmac_f32_e32 v239, v167, v231
	v_fmac_f32_e32 v240, v167, v232
	v_fmac_f32_e32 v241, v167, v233
	ds_write_b128 v247, v[238:241] offset:2112
	s_waitcnt vmcnt(8)
	v_mfma_f32_16x16x32_bf16 v[184:187], v[88:91], v[0:3], 0
	v_mfma_f32_16x16x32_bf16 v[188:191], v[88:91], v[8:11], 0
	v_mfma_f32_16x16x32_bf16 v[226:229], v[88:91], v[16:19], 0
	v_mfma_f32_16x16x32_bf16 v[230:233], v[88:91], v[24:27], 0
	v_mfma_f32_16x16x32_bf16 v[184:187], v[92:95], v[4:7], v[184:187]
	v_mfma_f32_16x16x32_bf16 v[188:191], v[92:95], v[12:15], v[188:191]
	v_mfma_f32_16x16x32_bf16 v[226:229], v[92:95], v[20:23], v[226:229]
	v_mfma_f32_16x16x32_bf16 v[230:233], v[92:95], v[28:31], v[230:233]
	v_max_f32_e32 v168, 0, v168
	v_max_f32_e32 v169, 0, v169
	v_max_f32_e32 v170, 0, v170
	v_max_f32_e32 v171, 0, v171
	v_max_f32_e32 v172, 0, v172
	v_max_f32_e32 v173, 0, v173
	v_max_f32_e32 v174, 0, v174
	v_max_f32_e32 v175, 0, v175
	v_max_f32_e32 v176, 0, v176
	v_max_f32_e32 v177, 0, v177
	v_max_f32_e32 v178, 0, v178
	v_max_f32_e32 v179, 0, v179
	v_max_f32_e32 v180, 0, v180
	v_max_f32_e32 v181, 0, v181
	v_max_f32_e32 v182, 0, v182
	v_max_f32_e32 v183, 0, v183
	v_fma_f32 v234, v164, v168, 0
	v_fma_f32 v235, v164, v169, 0
	v_fma_f32 v236, v164, v170, 0
	v_fma_f32 v237, v164, v171, 0
	v_fmac_f32_e32 v234, v165, v172
	v_fmac_f32_e32 v235, v165, v173
	v_fmac_f32_e32 v236, v165, v174
	v_fmac_f32_e32 v237, v165, v175
	v_fmac_f32_e32 v234, v166, v176
	v_fmac_f32_e32 v235, v166, v177
	v_fmac_f32_e32 v236, v166, v178
	v_fmac_f32_e32 v237, v166, v179
	v_fmac_f32_e32 v234, v167, v180
	v_fmac_f32_e32 v235, v167, v181
	v_fmac_f32_e32 v236, v167, v182
	v_fmac_f32_e32 v237, v167, v183
	ds_write_b128 v247, v[234:237] offset:2176
	s_waitcnt vmcnt(6)
	v_mfma_f32_16x16x32_bf16 v[168:171], v[96:99], v[0:3], 0
	v_mfma_f32_16x16x32_bf16 v[172:175], v[96:99], v[8:11], 0
	v_mfma_f32_16x16x32_bf16 v[176:179], v[96:99], v[16:19], 0
	v_mfma_f32_16x16x32_bf16 v[180:183], v[96:99], v[24:27], 0
	v_mfma_f32_16x16x32_bf16 v[168:171], v[100:103], v[4:7], v[168:171]
	v_mfma_f32_16x16x32_bf16 v[172:175], v[100:103], v[12:15], v[172:175]
	v_mfma_f32_16x16x32_bf16 v[176:179], v[100:103], v[20:23], v[176:179]
	v_mfma_f32_16x16x32_bf16 v[180:183], v[100:103], v[28:31], v[180:183]
	v_max_f32_e32 v184, 0, v184
	v_max_f32_e32 v185, 0, v185
	v_max_f32_e32 v186, 0, v186
	v_max_f32_e32 v187, 0, v187
	v_max_f32_e32 v188, 0, v188
	v_max_f32_e32 v189, 0, v189
	v_max_f32_e32 v190, 0, v190
	v_max_f32_e32 v191, 0, v191
	v_max_f32_e32 v226, 0, v226
	v_max_f32_e32 v227, 0, v227
	v_max_f32_e32 v228, 0, v228
	v_max_f32_e32 v229, 0, v229
	v_max_f32_e32 v230, 0, v230
	v_max_f32_e32 v231, 0, v231
	v_max_f32_e32 v232, 0, v232
	v_max_f32_e32 v233, 0, v233
	v_fma_f32 v238, v164, v184, 0
	v_fma_f32 v239, v164, v185, 0
	v_fma_f32 v240, v164, v186, 0
	v_fma_f32 v241, v164, v187, 0
	v_fmac_f32_e32 v238, v165, v188
	v_fmac_f32_e32 v239, v165, v189
	v_fmac_f32_e32 v240, v165, v190
	v_fmac_f32_e32 v241, v165, v191
	v_fmac_f32_e32 v238, v166, v226
	v_fmac_f32_e32 v239, v166, v227
	v_fmac_f32_e32 v240, v166, v228
	v_fmac_f32_e32 v241, v166, v229
	v_fmac_f32_e32 v238, v167, v230
	v_fmac_f32_e32 v239, v167, v231
	v_fmac_f32_e32 v240, v167, v232
	v_fmac_f32_e32 v241, v167, v233
	ds_write_b128 v247, v[238:241] offset:2240
	s_add_i32 s0, s7, 65
	s_cmp_gt_i32 s0, s4
	s_cbranch_scc1 .Lsc_x3_9
	s_waitcnt vmcnt(4)
	v_mfma_f32_16x16x32_bf16 v[184:187], v[104:107], v[0:3], 0
	v_mfma_f32_16x16x32_bf16 v[188:191], v[104:107], v[8:11], 0
	v_mfma_f32_16x16x32_bf16 v[226:229], v[104:107], v[16:19], 0
	v_mfma_f32_16x16x32_bf16 v[230:233], v[104:107], v[24:27], 0
	v_mfma_f32_16x16x32_bf16 v[184:187], v[108:111], v[4:7], v[184:187]
	v_mfma_f32_16x16x32_bf16 v[188:191], v[108:111], v[12:15], v[188:191]
	v_mfma_f32_16x16x32_bf16 v[226:229], v[108:111], v[20:23], v[226:229]
	v_mfma_f32_16x16x32_bf16 v[230:233], v[108:111], v[28:31], v[230:233]
	v_max_f32_e32 v168, 0, v168
	v_max_f32_e32 v169, 0, v169
	v_max_f32_e32 v170, 0, v170
	v_max_f32_e32 v171, 0, v171
	v_max_f32_e32 v172, 0, v172
	v_max_f32_e32 v173, 0, v173
	v_max_f32_e32 v174, 0, v174
	v_max_f32_e32 v175, 0, v175
	v_max_f32_e32 v176, 0, v176
	v_max_f32_e32 v177, 0, v177
	v_max_f32_e32 v178, 0, v178
	v_max_f32_e32 v179, 0, v179
	v_max_f32_e32 v180, 0, v180
	v_max_f32_e32 v181, 0, v181
	v_max_f32_e32 v182, 0, v182
	v_max_f32_e32 v183, 0, v183
	v_fma_f32 v234, v164, v168, 0
	v_fma_f32 v235, v164, v169, 0
	v_fma_f32 v236, v164, v170, 0
	v_fma_f32 v237, v164, v171, 0
	v_fmac_f32_e32 v234, v165, v172
	v_fmac_f32_e32 v235, v165, v173
	v_fmac_f32_e32 v236, v165, v174
	v_fmac_f32_e32 v237, v165, v175
	v_fmac_f32_e32 v234, v166, v176
	v_fmac_f32_e32 v235, v166, v177
	v_fmac_f32_e32 v236, v166, v178
	v_fmac_f32_e32 v237, v166, v179
	v_fmac_f32_e32 v234, v167, v180
	v_fmac_f32_e32 v235, v167, v181
	v_fmac_f32_e32 v236, v167, v182
	v_fmac_f32_e32 v237, v167, v183
	ds_write_b128 v247, v[234:237] offset:4096
	s_add_i32 s0, s7, 66
	s_cmp_gt_i32 s0, s4
	s_cbranch_scc1 .Lsc_x3_10
	s_waitcnt vmcnt(2)
	v_mfma_f32_16x16x32_bf16 v[168:171], v[112:115], v[0:3], 0
	v_mfma_f32_16x16x32_bf16 v[172:175], v[112:115], v[8:11], 0
	v_mfma_f32_16x16x32_bf16 v[176:179], v[112:115], v[16:19], 0
	v_mfma_f32_16x16x32_bf16 v[180:183], v[112:115], v[24:27], 0
	v_mfma_f32_16x16x32_bf16 v[168:171], v[116:119], v[4:7], v[168:171]
	v_mfma_f32_16x16x32_bf16 v[172:175], v[116:119], v[12:15], v[172:175]
	v_mfma_f32_16x16x32_bf16 v[176:179], v[116:119], v[20:23], v[176:179]
	v_mfma_f32_16x16x32_bf16 v[180:183], v[116:119], v[28:31], v[180:183]
	v_max_f32_e32 v184, 0, v184
	v_max_f32_e32 v185, 0, v185
	v_max_f32_e32 v186, 0, v186
	v_max_f32_e32 v187, 0, v187
	v_max_f32_e32 v188, 0, v188
	v_max_f32_e32 v189, 0, v189
	v_max_f32_e32 v190, 0, v190
	v_max_f32_e32 v191, 0, v191
	v_max_f32_e32 v226, 0, v226
	v_max_f32_e32 v227, 0, v227
	v_max_f32_e32 v228, 0, v228
	v_max_f32_e32 v229, 0, v229
	v_max_f32_e32 v230, 0, v230
	v_max_f32_e32 v231, 0, v231
	v_max_f32_e32 v232, 0, v232
	v_max_f32_e32 v233, 0, v233
	v_fma_f32 v238, v164, v184, 0
	v_fma_f32 v239, v164, v185, 0
	v_fma_f32 v240, v164, v186, 0
	v_fma_f32 v241, v164, v187, 0
	v_fmac_f32_e32 v238, v165, v188
	v_fmac_f32_e32 v239, v165, v189
	v_fmac_f32_e32 v240, v165, v190
	v_fmac_f32_e32 v241, v165, v191
	v_fmac_f32_e32 v238, v166, v226
	v_fmac_f32_e32 v239, v166, v227
	v_fmac_f32_e32 v240, v166, v228
	v_fmac_f32_e32 v241, v166, v229
	v_fmac_f32_e32 v238, v167, v230
	v_fmac_f32_e32 v239, v167, v231
	v_fmac_f32_e32 v240, v167, v232
	v_fmac_f32_e32 v241, v167, v233
	ds_write_b128 v247, v[238:241] offset:4160
	s_add_i32 s0, s7, 67
	s_cmp_gt_i32 s0, s4
	s_cbranch_scc1 .Lsc_x3_11
	s_waitcnt vmcnt(0)
	v_mfma_f32_16x16x32_bf16 v[184:187], v[120:123], v[0:3], 0
	v_mfma_f32_16x16x32_bf16 v[188:191], v[120:123], v[8:11], 0
	v_mfma_f32_16x16x32_bf16 v[226:229], v[120:123], v[16:19], 0
	v_mfma_f32_16x16x32_bf16 v[230:233], v[120:123], v[24:27], 0
	v_mfma_f32_16x16x32_bf16 v[184:187], v[124:127], v[4:7], v[184:187]
	v_mfma_f32_16x16x32_bf16 v[188:191], v[124:127], v[12:15], v[188:191]
	v_mfma_f32_16x16x32_bf16 v[226:229], v[124:127], v[20:23], v[226:229]
	v_mfma_f32_16x16x32_bf16 v[230:233], v[124:127], v[28:31], v[230:233]
	v_max_f32_e32 v168, 0, v168
	v_max_f32_e32 v169, 0, v169
	v_max_f32_e32 v170, 0, v170
	v_max_f32_e32 v171, 0, v171
	v_max_f32_e32 v172, 0, v172
	v_max_f32_e32 v173, 0, v173
	v_max_f32_e32 v174, 0, v174
	v_max_f32_e32 v175, 0, v175
	v_max_f32_e32 v176, 0, v176
	v_max_f32_e32 v177, 0, v177
	v_max_f32_e32 v178, 0, v178
	v_max_f32_e32 v179, 0, v179
	v_max_f32_e32 v180, 0, v180
	v_max_f32_e32 v181, 0, v181
	v_max_f32_e32 v182, 0, v182
	v_max_f32_e32 v183, 0, v183
	v_fma_f32 v234, v164, v168, 0
	v_fma_f32 v235, v164, v169, 0
	v_fma_f32 v236, v164, v170, 0
	v_fma_f32 v237, v164, v171, 0
	v_fmac_f32_e32 v234, v165, v172
	v_fmac_f32_e32 v235, v165, v173
	v_fmac_f32_e32 v236, v165, v174
	v_fmac_f32_e32 v237, v165, v175
	v_fmac_f32_e32 v234, v166, v176
	v_fmac_f32_e32 v235, v166, v177
	v_fmac_f32_e32 v236, v166, v178
	v_fmac_f32_e32 v237, v166, v179
	v_fmac_f32_e32 v234, v167, v180
	v_fmac_f32_e32 v235, v167, v181
	v_fmac_f32_e32 v236, v167, v182
	v_fmac_f32_e32 v237, v167, v183
	ds_write_b128 v247, v[234:237] offset:4224
	v_max_f32_e32 v184, 0, v184
	v_max_f32_e32 v185, 0, v185
	v_max_f32_e32 v186, 0, v186
	v_max_f32_e32 v187, 0, v187
	v_max_f32_e32 v188, 0, v188
	v_max_f32_e32 v189, 0, v189
	v_max_f32_e32 v190, 0, v190
	v_max_f32_e32 v191, 0, v191
	v_max_f32_e32 v226, 0, v226
	v_max_f32_e32 v227, 0, v227
	v_max_f32_e32 v228, 0, v228
	v_max_f32_e32 v229, 0, v229
	v_max_f32_e32 v230, 0, v230
	v_max_f32_e32 v231, 0, v231
	v_max_f32_e32 v232, 0, v232
	v_max_f32_e32 v233, 0, v233
	v_fma_f32 v238, v164, v184, 0
	v_fma_f32 v239, v164, v185, 0
	v_fma_f32 v240, v164, v186, 0
	v_fma_f32 v241, v164, v187, 0
	v_fmac_f32_e32 v238, v165, v188
	v_fmac_f32_e32 v239, v165, v189
	v_fmac_f32_e32 v240, v165, v190
	v_fmac_f32_e32 v241, v165, v191
	v_fmac_f32_e32 v238, v166, v226
	v_fmac_f32_e32 v239, v166, v227
	v_fmac_f32_e32 v240, v166, v228
	v_fmac_f32_e32 v241, v166, v229
	v_fmac_f32_e32 v238, v167, v230
	v_fmac_f32_e32 v239, v167, v231
	v_fmac_f32_e32 v240, v167, v232
	v_fmac_f32_e32 v241, v167, v233
	ds_write_b128 v247, v[238:241] offset:4288
	s_branch .LBB0_820
.Lsc_x3_9:
	s_nop 9
	v_max_f32_e32 v168, 0, v168
	v_max_f32_e32 v169, 0, v169
	v_max_f32_e32 v170, 0, v170
	v_max_f32_e32 v171, 0, v171
	v_max_f32_e32 v172, 0, v172
	v_max_f32_e32 v173, 0, v173
	v_max_f32_e32 v174, 0, v174
	v_max_f32_e32 v175, 0, v175
	v_max_f32_e32 v176, 0, v176
	v_max_f32_e32 v177, 0, v177
	v_max_f32_e32 v178, 0, v178
	v_max_f32_e32 v179, 0, v179
	v_max_f32_e32 v180, 0, v180
	v_max_f32_e32 v181, 0, v181
	v_max_f32_e32 v182, 0, v182
	v_max_f32_e32 v183, 0, v183
	v_fma_f32 v234, v164, v168, 0
	v_fma_f32 v235, v164, v169, 0
	v_fma_f32 v236, v164, v170, 0
	v_fma_f32 v237, v164, v171, 0
	v_fmac_f32_e32 v234, v165, v172
	v_fmac_f32_e32 v235, v165, v173
	v_fmac_f32_e32 v236, v165, v174
	v_fmac_f32_e32 v237, v165, v175
	v_fmac_f32_e32 v234, v166, v176
	v_fmac_f32_e32 v235, v166, v177
	v_fmac_f32_e32 v236, v166, v178
	v_fmac_f32_e32 v237, v166, v179
	v_fmac_f32_e32 v234, v167, v180
	v_fmac_f32_e32 v235, v167, v181
	v_fmac_f32_e32 v236, v167, v182
	v_fmac_f32_e32 v237, v167, v183
	ds_write_b128 v247, v[234:237] offset:4096
	s_branch .LBB0_820
.Lsc_x3_10:
	s_nop 9
	v_max_f32_e32 v184, 0, v184
	v_max_f32_e32 v185, 0, v185
	v_max_f32_e32 v186, 0, v186
	v_max_f32_e32 v187, 0, v187
	v_max_f32_e32 v188, 0, v188
	v_max_f32_e32 v189, 0, v189
	v_max_f32_e32 v190, 0, v190
	v_max_f32_e32 v191, 0, v191
	v_max_f32_e32 v226, 0, v226
	v_max_f32_e32 v227, 0, v227
	v_max_f32_e32 v228, 0, v228
	v_max_f32_e32 v229, 0, v229
	v_max_f32_e32 v230, 0, v230
	v_max_f32_e32 v231, 0, v231
	v_max_f32_e32 v232, 0, v232
	v_max_f32_e32 v233, 0, v233
	v_fma_f32 v238, v164, v184, 0
	v_fma_f32 v239, v164, v185, 0
	v_fma_f32 v240, v164, v186, 0
	v_fma_f32 v241, v164, v187, 0
	v_fmac_f32_e32 v238, v165, v188
	v_fmac_f32_e32 v239, v165, v189
	v_fmac_f32_e32 v240, v165, v190
	v_fmac_f32_e32 v241, v165, v191
	v_fmac_f32_e32 v238, v166, v226
	v_fmac_f32_e32 v239, v166, v227
	v_fmac_f32_e32 v240, v166, v228
	v_fmac_f32_e32 v241, v166, v229
	v_fmac_f32_e32 v238, v167, v230
	v_fmac_f32_e32 v239, v167, v231
	v_fmac_f32_e32 v240, v167, v232
	v_fmac_f32_e32 v241, v167, v233
	ds_write_b128 v247, v[238:241] offset:4160
	s_branch .LBB0_820
.Lsc_x3_11:
	s_nop 9
	v_max_f32_e32 v168, 0, v168
	v_max_f32_e32 v169, 0, v169
	v_max_f32_e32 v170, 0, v170
	v_max_f32_e32 v171, 0, v171
	v_max_f32_e32 v172, 0, v172
	v_max_f32_e32 v173, 0, v173
	v_max_f32_e32 v174, 0, v174
	v_max_f32_e32 v175, 0, v175
	v_max_f32_e32 v176, 0, v176
	v_max_f32_e32 v177, 0, v177
	v_max_f32_e32 v178, 0, v178
	v_max_f32_e32 v179, 0, v179
	v_max_f32_e32 v180, 0, v180
	v_max_f32_e32 v181, 0, v181
	v_max_f32_e32 v182, 0, v182
	v_max_f32_e32 v183, 0, v183
	v_fma_f32 v234, v164, v168, 0
	v_fma_f32 v235, v164, v169, 0
	v_fma_f32 v236, v164, v170, 0
	v_fma_f32 v237, v164, v171, 0
	v_fmac_f32_e32 v234, v165, v172
	v_fmac_f32_e32 v235, v165, v173
	v_fmac_f32_e32 v236, v165, v174
	v_fmac_f32_e32 v237, v165, v175
	v_fmac_f32_e32 v234, v166, v176
	v_fmac_f32_e32 v235, v166, v177
	v_fmac_f32_e32 v236, v166, v178
	v_fmac_f32_e32 v237, v166, v179
	v_fmac_f32_e32 v234, v167, v180
	v_fmac_f32_e32 v235, v167, v181
	v_fmac_f32_e32 v236, v167, v182
	v_fmac_f32_e32 v237, v167, v183
	ds_write_b128 v247, v[234:237] offset:4224
	s_branch .LBB0_820
.LBB0_820:
	s_waitcnt vmcnt(0) lgkmcnt(0)
	v_mov_b32_e32 v65, 0
	s_barrier
	s_lshl_b32 s26, s5, 1
	s_mov_b32 s36, 0xec800000
	s_mov_b32 s37, 0x6c800000
	v_mov_b32_e32 v149, 0xd1800000
	v_lshlrev_b32_e32 v152, 2, v197
	v_mov_b32_e32 v154, 0x3f803f80
	v_mov_b32_e32 v155, 0x3f803f80
	v_mov_b32_e32 v156, 0x3f803f80
	v_mov_b32_e32 v157, 0x3f803f80
	s_mov_b32 s4, 0

.Lsel_nosnap1:
	s_xor_b32 s1, s7, 0x80000000
	s_not_b32 s0, s7
	s_bitcmp1_b32 s7, 31
	s_cselect_b32 s0, s1, s0
	v_mov_b32_e32 v142, s0
	v_mul_f32_e32 v142, s37, v142
	v_fma_f32 v134, v102, s36, v142 clamp
	v_fma_f32 v135, v103, s36, v142 clamp
	v_fma_f32 v136, v104, s36, v142 clamp
	v_fma_f32 v137, v105, s36, v142 clamp
	v_fma_f32 v158, v106, s36, v142 clamp
	v_fma_f32 v159, v107, s36, v142 clamp
	v_fma_f32 v160, v108, s36, v142 clamp
	v_fma_f32 v161, v109, s36, v142 clamp
	v_mfma_f32_16x16x32_bf16 v[138:141], v[154:157], v[134:137], 0
	v_fma_f32 v134, v110, s36, v142 clamp
	v_fma_f32 v135, v111, s36, v142 clamp
	v_fma_f32 v136, v112, s36, v142 clamp
	v_fma_f32 v137, v113, s36, v142 clamp
	v_mfma_f32_16x16x32_bf16 v[138:141], v[154:157], v[158:161], v[138:141]
	v_fma_f32 v158, v114, s36, v142 clamp
	v_fma_f32 v159, v115, s36, v142 clamp
	v_fma_f32 v160, v116, s36, v142 clamp
	v_fma_f32 v161, v117, s36, v142 clamp
	v_mfma_f32_16x16x32_bf16 v[138:141], v[154:157], v[134:137], v[138:141]
	v_fma_f32 v134, v118, s36, v142 clamp
	v_fma_f32 v135, v119, s36, v142 clamp
	v_fma_f32 v136, v120, s36, v142 clamp
	v_fma_f32 v137, v121, s36, v142 clamp
	v_mfma_f32_16x16x32_bf16 v[138:141], v[154:157], v[158:161], v[138:141]
	v_fma_f32 v158, v122, s36, v142 clamp
	v_fma_f32 v159, v123, s36, v142 clamp
	v_fma_f32 v160, v124, s36, v142 clamp
	v_fma_f32 v161, v125, s36, v142 clamp
	v_mfma_f32_16x16x32_bf16 v[138:141], v[154:157], v[134:137], v[138:141]
	v_fma_f32 v134, v126, s36, v142 clamp
	v_fma_f32 v135, v127, s36, v142 clamp
	v_fma_f32 v136, v128, s36, v142 clamp
	v_fma_f32 v137, v129, s36, v142 clamp
	v_mfma_f32_16x16x32_bf16 v[138:141], v[154:157], v[158:161], v[138:141]
	v_fma_f32 v158, v130, s36, v142 clamp
	v_fma_f32 v159, v131, s36, v142 clamp
	v_fma_f32 v160, v132, s36, v142 clamp
	v_fma_f32 v161, v133, s36, v142 clamp
	v_mfma_f32_16x16x32_bf16 v[138:141], v[154:157], v[134:137], v[138:141]
	s_nop 0
	v_mfma_f32_16x16x32_bf16 v[138:141], v[154:157], v[158:161], v[138:141]
	s_nop 7
	v_add_f32_dpp v138, v138, v138 quad_perm:[1,0,3,2] row_mask:0xf bank_mask:0xf bound_ctrl:1
	s_nop 1
	v_add_f32_dpp v138, v138, v138 quad_perm:[2,3,0,1] row_mask:0xf bank_mask:0xf bound_ctrl:1
	s_nop 1
	v_add_f32_dpp v138, v138, v138 row_half_mirror row_mask:0xf bank_mask:0xf bound_ctrl:1
	s_nop 1
	v_add_f32_dpp v138, v138, v138 row_mirror row_mask:0xf bank_mask:0xf bound_ctrl:1
	v_cvt_u32_f32_e32 v138, v138
	s_nop 0
	v_readfirstlane_b32 s0, v138
	s_sub_i32 s0, 0x800, s0
	s_cmpk_lt_u32 s0, 0x100
	s_cbranch_scc1 .Lsel_bis_hi
	s_mov_b32 s29, s6
	s_mov_b32 s31, s0
	s_cmpk_eq_u32 s0, 0x100
	s_cbranch_scc0 .Lsel_bis
	s_branch .Lsel_bis_done

.Lsel_ties:
	v_mov_b32_e32 v150, s0
	v_mul_f32_e32 v142, s37, v150
	v_fma_f32 v134, v102, s37, -v142 clamp
	v_fma_f32 v135, v103, s37, -v142 clamp
	v_fma_f32 v136, v104, s37, -v142 clamp
	v_fma_f32 v137, v105, s37, -v142 clamp
	v_fma_f32 v158, v106, s37, -v142 clamp
	v_fma_f32 v159, v107, s37, -v142 clamp
	v_fma_f32 v160, v108, s37, -v142 clamp
	v_fma_f32 v161, v109, s37, -v142 clamp
	v_mfma_f32_16x16x32_bf16 v[138:141], v[154:157], v[134:137], 0
	v_fma_f32 v134, v110, s37, -v142 clamp
	v_fma_f32 v135, v111, s37, -v142 clamp
	v_fma_f32 v136, v112, s37, -v142 clamp
	v_fma_f32 v137, v113, s37, -v142 clamp
	v_mfma_f32_16x16x32_bf16 v[138:141], v[154:157], v[158:161], v[138:141]
	v_fma_f32 v158, v114, s37, -v142 clamp
	v_fma_f32 v159, v115, s37, -v142 clamp
	v_fma_f32 v160, v116, s37, -v142 clamp
	v_fma_f32 v161, v117, s37, -v142 clamp
	v_mfma_f32_16x16x32_bf16 v[138:141], v[154:157], v[134:137], v[138:141]
	v_fma_f32 v134, v118, s37, -v142 clamp
	v_fma_f32 v135, v119, s37, -v142 clamp
	v_fma_f32 v136, v120, s37, -v142 clamp
	v_fma_f32 v137, v121, s37, -v142 clamp
	v_mfma_f32_16x16x32_bf16 v[138:141], v[154:157], v[158:161], v[138:141]
	v_fma_f32 v158, v122, s37, -v142 clamp
	v_fma_f32 v159, v123, s37, -v142 clamp
	v_fma_f32 v160, v124, s37, -v142 clamp
	v_fma_f32 v161, v125, s37, -v142 clamp
	v_mfma_f32_16x16x32_bf16 v[138:141], v[154:157], v[134:137], v[138:141]
	v_fma_f32 v134, v126, s37, -v142 clamp
	v_fma_f32 v135, v127, s37, -v142 clamp
	v_fma_f32 v136, v128, s37, -v142 clamp
	v_fma_f32 v137, v129, s37, -v142 clamp
	v_mfma_f32_16x16x32_bf16 v[138:141], v[154:157], v[158:161], v[138:141]
	v_fma_f32 v158, v130, s37, -v142 clamp
	v_fma_f32 v159, v131, s37, -v142 clamp
	v_fma_f32 v160, v132, s37, -v142 clamp
	v_fma_f32 v161, v133, s37, -v142 clamp
	v_mfma_f32_16x16x32_bf16 v[138:141], v[154:157], v[134:137], v[138:141]
	s_nop 0
	v_mfma_f32_16x16x32_bf16 v[138:141], v[154:157], v[158:161], v[138:141]
	s_nop 7
	v_add_f32_dpp v138, v138, v138 quad_perm:[1,0,3,2] row_mask:0xf bank_mask:0xf bound_ctrl:1
	s_nop 1
	v_add_f32_dpp v138, v138, v138 quad_perm:[2,3,0,1] row_mask:0xf bank_mask:0xf bound_ctrl:1
	s_nop 1
	v_add_f32_dpp v138, v138, v138 row_half_mirror row_mask:0xf bank_mask:0xf bound_ctrl:1
	s_nop 1
	v_add_f32_dpp v138, v138, v138 row_mirror row_mask:0xf bank_mask:0xf bound_ctrl:1
	v_cvt_u32_f32_e32 v138, v138
	s_nop 0
	v_readfirstlane_b32 s0, v138
	s_sub_i32 s38, 0x100, s0
	s_mov_b32 s39, 0
	v_mov_b32_e32 v146, 0
	v_cmp_eq_f32_e64 s[42:43], v102, v150
	v_fma_f32 v134, v102, s37, -v142 clamp
	v_cvt_u32_f32_e32 v134, v134
	v_mbcnt_lo_u32_b32 v135, s42, 0
	v_mbcnt_hi_u32_b32 v135, s43, v135
	v_add_u32_e32 v135, s39, v135
	v_cmp_gt_u32_e32 vcc, s38, v135
	s_nop 1
	s_and_b64 vcc, vcc, s[42:43]
	s_nop 1
	v_cndmask_b32_e64 v136, 0, 1, vcc
	v_or_b32_e32 v136, v136, v134
	v_lshl_or_b32 v146, v136, 0, v146
	s_bcnt1_i32_b64 s0, s[42:43]
	s_add_i32 s39, s39, s0
	v_cmp_eq_f32_e64 s[42:43], v103, v150
	v_fma_f32 v134, v103, s37, -v142 clamp
	v_cvt_u32_f32_e32 v134, v134
	v_mbcnt_lo_u32_b32 v135, s42, 0
	v_mbcnt_hi_u32_b32 v135, s43, v135
	v_add_u32_e32 v135, s39, v135
	v_cmp_gt_u32_e32 vcc, s38, v135
	s_nop 1
	s_and_b64 vcc, vcc, s[42:43]
	s_nop 1
	v_cndmask_b32_e64 v136, 0, 1, vcc
	v_or_b32_e32 v136, v136, v134
	v_lshl_or_b32 v146, v136, 1, v146
	s_bcnt1_i32_b64 s0, s[42:43]
	s_add_i32 s39, s39, s0
	v_cmp_eq_f32_e64 s[42:43], v104, v150
	v_fma_f32 v134, v104, s37, -v142 clamp
	v_cvt_u32_f32_e32 v134, v134
	v_mbcnt_lo_u32_b32 v135, s42, 0
	v_mbcnt_hi_u32_b32 v135, s43, v135
	v_add_u32_e32 v135, s39, v135
	v_cmp_gt_u32_e32 vcc, s38, v135
	s_nop 1
	s_and_b64 vcc, vcc, s[42:43]
	s_nop 1
	v_cndmask_b32_e64 v136, 0, 1, vcc
	v_or_b32_e32 v136, v136, v134
	v_lshl_or_b32 v146, v136, 2, v146
	s_bcnt1_i32_b64 s0, s[42:43]
	s_add_i32 s39, s39, s0
	v_cmp_eq_f32_e64 s[42:43], v105, v150
	v_fma_f32 v134, v105, s37, -v142 clamp
	v_cvt_u32_f32_e32 v134, v134
	v_mbcnt_lo_u32_b32 v135, s42, 0
	v_mbcnt_hi_u32_b32 v135, s43, v135
	v_add_u32_e32 v135, s39, v135
	v_cmp_gt_u32_e32 vcc, s38, v135
	s_nop 1
	s_and_b64 vcc, vcc, s[42:43]
	s_nop 1
	v_cndmask_b32_e64 v136, 0, 1, vcc
	v_or_b32_e32 v136, v136, v134
	v_lshl_or_b32 v146, v136, 3, v146
	s_bcnt1_i32_b64 s0, s[42:43]
	s_add_i32 s39, s39, s0
	v_cmp_eq_f32_e64 s[42:43], v106, v150
	v_fma_f32 v134, v106, s37, -v142 clamp
	v_cvt_u32_f32_e32 v134, v134
	v_mbcnt_lo_u32_b32 v135, s42, 0
	v_mbcnt_hi_u32_b32 v135, s43, v135
	v_add_u32_e32 v135, s39, v135
	v_cmp_gt_u32_e32 vcc, s38, v135
	s_nop 1
	s_and_b64 vcc, vcc, s[42:43]
	s_nop 1
	v_cndmask_b32_e64 v136, 0, 1, vcc
	v_or_b32_e32 v136, v136, v134
	v_lshl_or_b32 v146, v136, 4, v146
	s_bcnt1_i32_b64 s0, s[42:43]
	s_add_i32 s39, s39, s0
	v_cmp_eq_f32_e64 s[42:43], v107, v150
	v_fma_f32 v134, v107, s37, -v142 clamp
	v_cvt_u32_f32_e32 v134, v134
	v_mbcnt_lo_u32_b32 v135, s42, 0
	v_mbcnt_hi_u32_b32 v135, s43, v135
	v_add_u32_e32 v135, s39, v135
	v_cmp_gt_u32_e32 vcc, s38, v135
	s_nop 1
	s_and_b64 vcc, vcc, s[42:43]
	s_nop 1
	v_cndmask_b32_e64 v136, 0, 1, vcc
	v_or_b32_e32 v136, v136, v134
	v_lshl_or_b32 v146, v136, 5, v146
	s_bcnt1_i32_b64 s0, s[42:43]
	s_add_i32 s39, s39, s0
	v_cmp_eq_f32_e64 s[42:43], v108, v150
	v_fma_f32 v134, v108, s37, -v142 clamp
	v_cvt_u32_f32_e32 v134, v134
	v_mbcnt_lo_u32_b32 v135, s42, 0
	v_mbcnt_hi_u32_b32 v135, s43, v135
	v_add_u32_e32 v135, s39, v135
	v_cmp_gt_u32_e32 vcc, s38, v135
	s_nop 1
	s_and_b64 vcc, vcc, s[42:43]
	s_nop 1
	v_cndmask_b32_e64 v136, 0, 1, vcc
	v_or_b32_e32 v136, v136, v134
	v_lshl_or_b32 v146, v136, 6, v146
	s_bcnt1_i32_b64 s0, s[42:43]
	s_add_i32 s39, s39, s0
	v_cmp_eq_f32_e64 s[42:43], v109, v150
	v_fma_f32 v134, v109, s37, -v142 clamp
	v_cvt_u32_f32_e32 v134, v134
	v_mbcnt_lo_u32_b32 v135, s42, 0
	v_mbcnt_hi_u32_b32 v135, s43, v135
	v_add_u32_e32 v135, s39, v135
	v_cmp_gt_u32_e32 vcc, s38, v135
	s_nop 1
	s_and_b64 vcc, vcc, s[42:43]
	s_nop 1
	v_cndmask_b32_e64 v136, 0, 1, vcc
	v_or_b32_e32 v136, v136, v134
	v_lshl_or_b32 v146, v136, 7, v146
	s_bcnt1_i32_b64 s0, s[42:43]
	s_add_i32 s39, s39, s0
	v_cmp_eq_f32_e64 s[42:43], v110, v150
	v_fma_f32 v134, v110, s37, -v142 clamp
	v_cvt_u32_f32_e32 v134, v134
	v_mbcnt_lo_u32_b32 v135, s42, 0
	v_mbcnt_hi_u32_b32 v135, s43, v135
	v_add_u32_e32 v135, s39, v135
	v_cmp_gt_u32_e32 vcc, s38, v135
	s_nop 1
	s_and_b64 vcc, vcc, s[42:43]
	s_nop 1
	v_cndmask_b32_e64 v136, 0, 1, vcc
	v_or_b32_e32 v136, v136, v134
	v_lshl_or_b32 v146, v136, 8, v146
	s_bcnt1_i32_b64 s0, s[42:43]
	s_add_i32 s39, s39, s0
	v_cmp_eq_f32_e64 s[42:43], v111, v150
	v_fma_f32 v134, v111, s37, -v142 clamp
	v_cvt_u32_f32_e32 v134, v134
	v_mbcnt_lo_u32_b32 v135, s42, 0
	v_mbcnt_hi_u32_b32 v135, s43, v135
	v_add_u32_e32 v135, s39, v135
	v_cmp_gt_u32_e32 vcc, s38, v135
	s_nop 1
	s_and_b64 vcc, vcc, s[42:43]
	s_nop 1
	v_cndmask_b32_e64 v136, 0, 1, vcc
	v_or_b32_e32 v136, v136, v134
	v_lshl_or_b32 v146, v136, 9, v146
	s_bcnt1_i32_b64 s0, s[42:43]
	s_add_i32 s39, s39, s0
	v_cmp_eq_f32_e64 s[42:43], v112, v150
	v_fma_f32 v134, v112, s37, -v142 clamp
	v_cvt_u32_f32_e32 v134, v134
	v_mbcnt_lo_u32_b32 v135, s42, 0
	v_mbcnt_hi_u32_b32 v135, s43, v135
	v_add_u32_e32 v135, s39, v135
	v_cmp_gt_u32_e32 vcc, s38, v135
	s_nop 1
	s_and_b64 vcc, vcc, s[42:43]
	s_nop 1
	v_cndmask_b32_e64 v136, 0, 1, vcc
	v_or_b32_e32 v136, v136, v134
	v_lshl_or_b32 v146, v136, 10, v146
	s_bcnt1_i32_b64 s0, s[42:43]
	s_add_i32 s39, s39, s0
	v_cmp_eq_f32_e64 s[42:43], v113, v150
	v_fma_f32 v134, v113, s37, -v142 clamp
	v_cvt_u32_f32_e32 v134, v134
	v_mbcnt_lo_u32_b32 v135, s42, 0
	v_mbcnt_hi_u32_b32 v135, s43, v135
	v_add_u32_e32 v135, s39, v135
	v_cmp_gt_u32_e32 vcc, s38, v135
	s_nop 1
	s_and_b64 vcc, vcc, s[42:43]
	s_nop 1
	v_cndmask_b32_e64 v136, 0, 1, vcc
	v_or_b32_e32 v136, v136, v134
	v_lshl_or_b32 v146, v136, 11, v146
	s_bcnt1_i32_b64 s0, s[42:43]
	s_add_i32 s39, s39, s0
	v_cmp_eq_f32_e64 s[42:43], v114, v150
	v_fma_f32 v134, v114, s37, -v142 clamp
	v_cvt_u32_f32_e32 v134, v134
	v_mbcnt_lo_u32_b32 v135, s42, 0
	v_mbcnt_hi_u32_b32 v135, s43, v135
	v_add_u32_e32 v135, s39, v135
	v_cmp_gt_u32_e32 vcc, s38, v135
	s_nop 1
	s_and_b64 vcc, vcc, s[42:43]
	s_nop 1
	v_cndmask_b32_e64 v136, 0, 1, vcc
	v_or_b32_e32 v136, v136, v134
	v_lshl_or_b32 v146, v136, 12, v146
	s_bcnt1_i32_b64 s0, s[42:43]
	s_add_i32 s39, s39, s0
	v_cmp_eq_f32_e64 s[42:43], v115, v150
	v_fma_f32 v134, v115, s37, -v142 clamp
	v_cvt_u32_f32_e32 v134, v134
	v_mbcnt_lo_u32_b32 v135, s42, 0
	v_mbcnt_hi_u32_b32 v135, s43, v135
	v_add_u32_e32 v135, s39, v135
	v_cmp_gt_u32_e32 vcc, s38, v135
	s_nop 1
	s_and_b64 vcc, vcc, s[42:43]
	s_nop 1
	v_cndmask_b32_e64 v136, 0, 1, vcc
	v_or_b32_e32 v136, v136, v134
	v_lshl_or_b32 v146, v136, 13, v146
	s_bcnt1_i32_b64 s0, s[42:43]
	s_add_i32 s39, s39, s0
	v_cmp_eq_f32_e64 s[42:43], v116, v150
	v_fma_f32 v134, v116, s37, -v142 clamp
	v_cvt_u32_f32_e32 v134, v134
	v_mbcnt_lo_u32_b32 v135, s42, 0
	v_mbcnt_hi_u32_b32 v135, s43, v135
	v_add_u32_e32 v135, s39, v135
	v_cmp_gt_u32_e32 vcc, s38, v135
	s_nop 1
	s_and_b64 vcc, vcc, s[42:43]
	s_nop 1
	v_cndmask_b32_e64 v136, 0, 1, vcc
	v_or_b32_e32 v136, v136, v134
	v_lshl_or_b32 v146, v136, 14, v146
	s_bcnt1_i32_b64 s0, s[42:43]
	s_add_i32 s39, s39, s0
	v_cmp_eq_f32_e64 s[42:43], v117, v150
	v_fma_f32 v134, v117, s37, -v142 clamp
	v_cvt_u32_f32_e32 v134, v134
	v_mbcnt_lo_u32_b32 v135, s42, 0
	v_mbcnt_hi_u32_b32 v135, s43, v135
	v_add_u32_e32 v135, s39, v135
	v_cmp_gt_u32_e32 vcc, s38, v135
	s_nop 1
	s_and_b64 vcc, vcc, s[42:43]
	s_nop 1
	v_cndmask_b32_e64 v136, 0, 1, vcc
	v_or_b32_e32 v136, v136, v134
	v_lshl_or_b32 v146, v136, 15, v146
	s_bcnt1_i32_b64 s0, s[42:43]
	s_add_i32 s39, s39, s0
	v_cmp_eq_f32_e64 s[42:43], v118, v150
	v_fma_f32 v134, v118, s37, -v142 clamp
	v_cvt_u32_f32_e32 v134, v134
	v_mbcnt_lo_u32_b32 v135, s42, 0
	v_mbcnt_hi_u32_b32 v135, s43, v135
	v_add_u32_e32 v135, s39, v135
	v_cmp_gt_u32_e32 vcc, s38, v135
	s_nop 1
	s_and_b64 vcc, vcc, s[42:43]
	s_nop 1
	v_cndmask_b32_e64 v136, 0, 1, vcc
	v_or_b32_e32 v136, v136, v134
	v_lshl_or_b32 v146, v136, 16, v146
	s_bcnt1_i32_b64 s0, s[42:43]
	s_add_i32 s39, s39, s0
	v_cmp_eq_f32_e64 s[42:43], v119, v150
	v_fma_f32 v134, v119, s37, -v142 clamp
	v_cvt_u32_f32_e32 v134, v134
	v_mbcnt_lo_u32_b32 v135, s42, 0
	v_mbcnt_hi_u32_b32 v135, s43, v135
	v_add_u32_e32 v135, s39, v135
	v_cmp_gt_u32_e32 vcc, s38, v135
	s_nop 1
	s_and_b64 vcc, vcc, s[42:43]
	s_nop 1
	v_cndmask_b32_e64 v136, 0, 1, vcc
	v_or_b32_e32 v136, v136, v134
	v_lshl_or_b32 v146, v136, 17, v146
	s_bcnt1_i32_b64 s0, s[42:43]
	s_add_i32 s39, s39, s0
	v_cmp_eq_f32_e64 s[42:43], v120, v150
	v_fma_f32 v134, v120, s37, -v142 clamp
	v_cvt_u32_f32_e32 v134, v134
	v_mbcnt_lo_u32_b32 v135, s42, 0
	v_mbcnt_hi_u32_b32 v135, s43, v135
	v_add_u32_e32 v135, s39, v135
	v_cmp_gt_u32_e32 vcc, s38, v135
	s_nop 1
	s_and_b64 vcc, vcc, s[42:43]
	s_nop 1
	v_cndmask_b32_e64 v136, 0, 1, vcc
	v_or_b32_e32 v136, v136, v134
	v_lshl_or_b32 v146, v136, 18, v146
	s_bcnt1_i32_b64 s0, s[42:43]
	s_add_i32 s39, s39, s0
	v_cmp_eq_f32_e64 s[42:43], v121, v150
	v_fma_f32 v134, v121, s37, -v142 clamp
	v_cvt_u32_f32_e32 v134, v134
	v_mbcnt_lo_u32_b32 v135, s42, 0
	v_mbcnt_hi_u32_b32 v135, s43, v135
	v_add_u32_e32 v135, s39, v135
	v_cmp_gt_u32_e32 vcc, s38, v135
	s_nop 1
	s_and_b64 vcc, vcc, s[42:43]
	s_nop 1
	v_cndmask_b32_e64 v136, 0, 1, vcc
	v_or_b32_e32 v136, v136, v134
	v_lshl_or_b32 v146, v136, 19, v146
	s_bcnt1_i32_b64 s0, s[42:43]
	s_add_i32 s39, s39, s0
	v_cmp_eq_f32_e64 s[42:43], v122, v150
	v_fma_f32 v134, v122, s37, -v142 clamp
	v_cvt_u32_f32_e32 v134, v134
	v_mbcnt_lo_u32_b32 v135, s42, 0
	v_mbcnt_hi_u32_b32 v135, s43, v135
	v_add_u32_e32 v135, s39, v135
	v_cmp_gt_u32_e32 vcc, s38, v135
	s_nop 1
	s_and_b64 vcc, vcc, s[42:43]
	s_nop 1
	v_cndmask_b32_e64 v136, 0, 1, vcc
	v_or_b32_e32 v136, v136, v134
	v_lshl_or_b32 v146, v136, 20, v146
	s_bcnt1_i32_b64 s0, s[42:43]
	s_add_i32 s39, s39, s0
	v_cmp_eq_f32_e64 s[42:43], v123, v150
	v_fma_f32 v134, v123, s37, -v142 clamp
	v_cvt_u32_f32_e32 v134, v134
	v_mbcnt_lo_u32_b32 v135, s42, 0
	v_mbcnt_hi_u32_b32 v135, s43, v135
	v_add_u32_e32 v135, s39, v135
	v_cmp_gt_u32_e32 vcc, s38, v135
	s_nop 1
	s_and_b64 vcc, vcc, s[42:43]
	s_nop 1
	v_cndmask_b32_e64 v136, 0, 1, vcc
	v_or_b32_e32 v136, v136, v134
	v_lshl_or_b32 v146, v136, 21, v146
	s_bcnt1_i32_b64 s0, s[42:43]
	s_add_i32 s39, s39, s0
	v_cmp_eq_f32_e64 s[42:43], v124, v150
	v_fma_f32 v134, v124, s37, -v142 clamp
	v_cvt_u32_f32_e32 v134, v134
	v_mbcnt_lo_u32_b32 v135, s42, 0
	v_mbcnt_hi_u32_b32 v135, s43, v135
	v_add_u32_e32 v135, s39, v135
	v_cmp_gt_u32_e32 vcc, s38, v135
	s_nop 1
	s_and_b64 vcc, vcc, s[42:43]
	s_nop 1
	v_cndmask_b32_e64 v136, 0, 1, vcc
	v_or_b32_e32 v136, v136, v134
	v_lshl_or_b32 v146, v136, 22, v146
	s_bcnt1_i32_b64 s0, s[42:43]
	s_add_i32 s39, s39, s0
	v_cmp_eq_f32_e64 s[42:43], v125, v150
	v_fma_f32 v134, v125, s37, -v142 clamp
	v_cvt_u32_f32_e32 v134, v134
	v_mbcnt_lo_u32_b32 v135, s42, 0
	v_mbcnt_hi_u32_b32 v135, s43, v135
	v_add_u32_e32 v135, s39, v135
	v_cmp_gt_u32_e32 vcc, s38, v135
	s_nop 1
	s_and_b64 vcc, vcc, s[42:43]
	s_nop 1
	v_cndmask_b32_e64 v136, 0, 1, vcc
	v_or_b32_e32 v136, v136, v134
	v_lshl_or_b32 v146, v136, 23, v146
	s_bcnt1_i32_b64 s0, s[42:43]
	s_add_i32 s39, s39, s0
	v_cmp_eq_f32_e64 s[42:43], v126, v150
	v_fma_f32 v134, v126, s37, -v142 clamp
	v_cvt_u32_f32_e32 v134, v134
	v_mbcnt_lo_u32_b32 v135, s42, 0
	v_mbcnt_hi_u32_b32 v135, s43, v135
	v_add_u32_e32 v135, s39, v135
	v_cmp_gt_u32_e32 vcc, s38, v135
	s_nop 1
	s_and_b64 vcc, vcc, s[42:43]
	s_nop 1
	v_cndmask_b32_e64 v136, 0, 1, vcc
	v_or_b32_e32 v136, v136, v134
	v_lshl_or_b32 v146, v136, 24, v146
	s_bcnt1_i32_b64 s0, s[42:43]
	s_add_i32 s39, s39, s0
	v_cmp_eq_f32_e64 s[42:43], v127, v150
	v_fma_f32 v134, v127, s37, -v142 clamp
	v_cvt_u32_f32_e32 v134, v134
	v_mbcnt_lo_u32_b32 v135, s42, 0
	v_mbcnt_hi_u32_b32 v135, s43, v135
	v_add_u32_e32 v135, s39, v135
	v_cmp_gt_u32_e32 vcc, s38, v135
	s_nop 1
	s_and_b64 vcc, vcc, s[42:43]
	s_nop 1
	v_cndmask_b32_e64 v136, 0, 1, vcc
	v_or_b32_e32 v136, v136, v134
	v_lshl_or_b32 v146, v136, 25, v146
	s_bcnt1_i32_b64 s0, s[42:43]
	s_add_i32 s39, s39, s0
	v_cmp_eq_f32_e64 s[42:43], v128, v150
	v_fma_f32 v134, v128, s37, -v142 clamp
	v_cvt_u32_f32_e32 v134, v134
	v_mbcnt_lo_u32_b32 v135, s42, 0
	v_mbcnt_hi_u32_b32 v135, s43, v135
	v_add_u32_e32 v135, s39, v135
	v_cmp_gt_u32_e32 vcc, s38, v135
	s_nop 1
	s_and_b64 vcc, vcc, s[42:43]
	s_nop 1
	v_cndmask_b32_e64 v136, 0, 1, vcc
	v_or_b32_e32 v136, v136, v134
	v_lshl_or_b32 v146, v136, 26, v146
	s_bcnt1_i32_b64 s0, s[42:43]
	s_add_i32 s39, s39, s0
	v_cmp_eq_f32_e64 s[42:43], v129, v150
	v_fma_f32 v134, v129, s37, -v142 clamp
	v_cvt_u32_f32_e32 v134, v134
	v_mbcnt_lo_u32_b32 v135, s42, 0
	v_mbcnt_hi_u32_b32 v135, s43, v135
	v_add_u32_e32 v135, s39, v135
	v_cmp_gt_u32_e32 vcc, s38, v135
	s_nop 1
	s_and_b64 vcc, vcc, s[42:43]
	s_nop 1
	v_cndmask_b32_e64 v136, 0, 1, vcc
	v_or_b32_e32 v136, v136, v134
	v_lshl_or_b32 v146, v136, 27, v146
	s_bcnt1_i32_b64 s0, s[42:43]
	s_add_i32 s39, s39, s0
	v_cmp_eq_f32_e64 s[42:43], v130, v150
	v_fma_f32 v134, v130, s37, -v142 clamp
	v_cvt_u32_f32_e32 v134, v134
	v_mbcnt_lo_u32_b32 v135, s42, 0
	v_mbcnt_hi_u32_b32 v135, s43, v135
	v_add_u32_e32 v135, s39, v135
	v_cmp_gt_u32_e32 vcc, s38, v135
	s_nop 1
	s_and_b64 vcc, vcc, s[42:43]
	s_nop 1
	v_cndmask_b32_e64 v136, 0, 1, vcc
	v_or_b32_e32 v136, v136, v134
	v_lshl_or_b32 v146, v136, 28, v146
	s_bcnt1_i32_b64 s0, s[42:43]
	s_add_i32 s39, s39, s0
	v_cmp_eq_f32_e64 s[42:43], v131, v150
	v_fma_f32 v134, v131, s37, -v142 clamp
	v_cvt_u32_f32_e32 v134, v134
	v_mbcnt_lo_u32_b32 v135, s42, 0
	v_mbcnt_hi_u32_b32 v135, s43, v135
	v_add_u32_e32 v135, s39, v135
	v_cmp_gt_u32_e32 vcc, s38, v135
	s_nop 1
	s_and_b64 vcc, vcc, s[42:43]
	s_nop 1
	v_cndmask_b32_e64 v136, 0, 1, vcc
	v_or_b32_e32 v136, v136, v134
	v_lshl_or_b32 v146, v136, 29, v146
	s_bcnt1_i32_b64 s0, s[42:43]
	s_add_i32 s39, s39, s0
	v_cmp_eq_f32_e64 s[42:43], v132, v150
	v_fma_f32 v134, v132, s37, -v142 clamp
	v_cvt_u32_f32_e32 v134, v134
	v_mbcnt_lo_u32_b32 v135, s42, 0
	v_mbcnt_hi_u32_b32 v135, s43, v135
	v_add_u32_e32 v135, s39, v135
	v_cmp_gt_u32_e32 vcc, s38, v135
	s_nop 1
	s_and_b64 vcc, vcc, s[42:43]
	s_nop 1
	v_cndmask_b32_e64 v136, 0, 1, vcc
	v_or_b32_e32 v136, v136, v134
	v_lshl_or_b32 v146, v136, 30, v146
	s_bcnt1_i32_b64 s0, s[42:43]
	s_add_i32 s39, s39, s0
	v_cmp_eq_f32_e64 s[42:43], v133, v150
	v_fma_f32 v134, v133, s37, -v142 clamp
	v_cvt_u32_f32_e32 v134, v134
	v_mbcnt_lo_u32_b32 v135, s42, 0
	v_mbcnt_hi_u32_b32 v135, s43, v135
	v_add_u32_e32 v135, s39, v135
	v_cmp_gt_u32_e32 vcc, s38, v135
	s_nop 1
	s_and_b64 vcc, vcc, s[42:43]
	s_nop 1
	v_cndmask_b32_e64 v136, 0, 1, vcc
	v_or_b32_e32 v136, v136, v134
	v_lshl_or_b32 v146, v136, 31, v146
	s_bcnt1_i32_b64 s0, s[42:43]
	s_add_i32 s39, s39, s0
	s_branch .Lsel_store
